# GEMM epilogue 16-byte stores made write-through (sc1) so the barrier leader's L2 writeback has less dirty data
# baseline (speedup 1.0000x reference)
; #define LAS __attribute__((address_space(3)))
; __device__ __forceinline__ void unpack8(u32x4 w, float* f) { f[0] = bflo(w.x); f[1] = bfhi(w.x); f[2] = bflo(w.y); f[3] = bfhi(w.y); f[4] = bflo(w.z); f[5] = bfhi(w.z); f[6] = bflo(w.w); f[7] = bfhi(w.w); }
; __device__ __forceinline__ u32x4 pack8(const float* f) { u32x4 w; w.x = cvt_pk_bf16(f[0], f[1]); w.y = cvt_pk_bf16(f[2], f[3]); w.z = cvt_pk_bf16(f[4], f[5]); w.w = cvt_pk_bf16(f[6], f[7]); return w; }
;     __device__ __forceinline__ void operator()(const f32x4 (&acc)[2][2][4][2], const Unit& u, int wr, int wc, int fr, int fq, LAS unsigned char* lds, int par, int npm, int tid) const {
;         const int row0 = u.pm * BM + wr * 64 + fr, col0 = u.pn * BM + wc * 32 + 8 * fq;
;         u32x4 old[2][4][2];
; #pragma unroll
;         for (int ai = 0; ai < 2; ++ai)
; #pragma unroll
;             for (int m = 0; m < 4; ++m)
; #pragma unroll
;                 for (int bj = 0; bj < 2; ++bj) old[ai][m][bj] = *(const u32x4*)(Hb + (size_t)(row0 + ai * HALF + m * 16) * ldc + col0 + bj * HALF);
; #pragma unroll
;         for (int ai = 0; ai < 2; ++ai)
; #pragma unroll
;             for (int m = 0; m < 4; ++m) { const int row = row0 + ai * HALF + m * 16; bf16_t* hp = Hb + (size_t)row * ldc + col0;
;                 float part = 0.f;
; #pragma unroll
;                 for (int bj = 0; bj < 2; ++bj) { float o[8]; unpack8(old[ai][m][bj], o);
;                     const f32x4 a0 = acc[ai][bj][m][0], a1 = acc[ai][bj][m][1];
;                     float v[8] = {o[0] + a0[0], o[1] + a0[1], o[2] + a0[2], o[3] + a0[3], o[4] + a1[0], o[5] + a1[1], o[6] + a1[2], o[7] + a1[3]};
; #pragma unroll
;                     for (int k = 0; k < 8; ++k) part += v[k] * v[k];
;                     *(u32x4*)(hp + bj * HALF) = pack8(v); }
;                 part += __shfl_xor(part, 16); part += __shfl_xor(part, 32);
;                 if (fq == 0) atomicAdd(ssq + row, (unsigned long long)(part * 1048576.f)); }
.LBB0_120:
	v_lshl_or_b32 v212, s38, 8, v246
	v_lshl_add_u32 v228, s37, 8, v201
	v_ashrrev_i32_e32 v213, 31, v212
	v_readlane_b32 s14, v254, 8
	v_lshlrev_b64 v[230:231], 1, v[212:213]
	v_readlane_b32 s15, v254, 9
	v_ashrrev_i32_e32 v229, 31, v228
	v_lshlrev_b64 v[232:233], 12, v[228:229]
	v_lshl_add_u64 v[132:133], s[14:15], 0, v[230:231]
	v_lshl_add_u64 v[128:129], v[132:133], 0, v[232:233]
	flat_load_dwordx4 v[188:191], v[128:129]
	flat_load_dwordx4 v[184:187], v[128:129] offset:256
	v_or_b32_e32 v226, 16, v228
	v_ashrrev_i32_e32 v227, 31, v226
	v_lshlrev_b64 v[128:129], 12, v[226:227]
	v_or_b32_e32 v224, 32, v228
	v_lshl_add_u64 v[128:129], v[132:133], 0, v[128:129]
	v_ashrrev_i32_e32 v225, 31, v224
	flat_load_dwordx4 v[180:183], v[128:129]
	flat_load_dwordx4 v[176:179], v[128:129] offset:256
	v_lshlrev_b64 v[128:129], 12, v[224:225]
	v_or_b32_e32 v222, 48, v228
	v_lshl_add_u64 v[128:129], v[132:133], 0, v[128:129]
	v_ashrrev_i32_e32 v223, 31, v222
	flat_load_dwordx4 v[172:175], v[128:129]
	flat_load_dwordx4 v[168:171], v[128:129] offset:256
	v_lshlrev_b64 v[128:129], 12, v[222:223]
	v_add_u32_e32 v220, 0x80, v228
	v_lshl_add_u64 v[128:129], v[132:133], 0, v[128:129]
	v_ashrrev_i32_e32 v221, 31, v220
	flat_load_dwordx4 v[164:167], v[128:129]
	flat_load_dwordx4 v[160:163], v[128:129] offset:256
	v_lshlrev_b64 v[128:129], 12, v[220:221]
	v_add_u32_e32 v218, 0x90, v228
	v_lshl_add_u64 v[128:129], v[132:133], 0, v[128:129]
	v_ashrrev_i32_e32 v219, 31, v218
	flat_load_dwordx4 v[156:159], v[128:129]
	flat_load_dwordx4 v[152:155], v[128:129] offset:256
	v_lshlrev_b64 v[128:129], 12, v[218:219]
	v_add_u32_e32 v216, 0xa0, v228
	v_add_u32_e32 v214, 0xb0, v228
	v_lshl_add_u64 v[128:129], v[132:133], 0, v[128:129]
	v_ashrrev_i32_e32 v217, 31, v216
	v_ashrrev_i32_e32 v215, 31, v214
	flat_load_dwordx4 v[148:151], v[128:129]
	flat_load_dwordx4 v[144:147], v[128:129] offset:256
	v_lshlrev_b64 v[128:129], 12, v[216:217]
	v_lshlrev_b64 v[134:135], 12, v[214:215]
	v_lshl_add_u64 v[128:129], v[132:133], 0, v[128:129]
	v_lshl_add_u64 v[132:133], v[132:133], 0, v[134:135]
	flat_load_dwordx4 v[136:139], v[128:129]
	s_nop 0
	flat_load_dwordx4 v[128:131], v[128:129] offset:256
	s_nop 0
	flat_load_dwordx4 v[140:143], v[132:133]
	s_nop 0
	flat_load_dwordx4 v[132:135], v[132:133] offset:256
	v_lshl_add_u64 v[232:233], s[14:15], 0, v[232:233]
	v_lshl_add_u64 v[230:231], v[232:233], 0, v[230:231]
	s_waitcnt vmcnt(0) lgkmcnt(0)
	v_lshlrev_b32_e32 v193, 16, v188
	v_and_b32_e32 v188, 0xffff0000, v188
	v_lshlrev_b32_e32 v239, 16, v191
	v_and_b32_e32 v191, 0xffff0000, v191
	v_add_f32_e32 v125, v125, v188
	v_lshlrev_b32_e32 v232, 16, v189
	v_add_f32_e32 v124, v124, v193
	v_add_f32_e32 v123, v123, v191
	v_mul_f32_e32 v191, v125, v125
	v_and_b32_e32 v189, 0xffff0000, v189
	v_add_f32_e32 v126, v126, v232
	v_fmac_f32_e32 v191, v124, v124
	v_lshlrev_b32_e32 v233, 16, v190
	v_add_f32_e32 v127, v127, v189
	v_fmac_f32_e32 v191, v126, v126
	v_and_b32_e32 v190, 0xffff0000, v190
	v_add_f32_e32 v188, v120, v233
	v_fmac_f32_e32 v191, v127, v127
	v_add_f32_e32 v189, v121, v190
	v_fmac_f32_e32 v191, v188, v188
	v_add_f32_e32 v190, v122, v239
	v_fmac_f32_e32 v191, v189, v189
	v_fmac_f32_e32 v191, v190, v190
	v_cvt_pk_bf16_f32 v120, v124, v125
	v_fmac_f32_e32 v191, v123, v123
	v_cvt_pk_bf16_f32 v121, v126, v127
	v_cvt_pk_bf16_f32 v122, v188, v189
	v_cvt_pk_bf16_f32 v123, v190, v123
	flat_store_dwordx4 v[230:231], v[120:123] sc1
	v_lshlrev_b32_e32 v124, 16, v186
	v_and_b32_e32 v125, 0xffff0000, v186
	v_lshlrev_b32_e32 v120, 16, v184
	v_and_b32_e32 v121, 0xffff0000, v184
	v_add_f32_e32 v116, v116, v120
	v_lshlrev_b32_e32 v122, 16, v185
	v_add_f32_e32 v117, v117, v121
	v_fmac_f32_e32 v191, v116, v116
	v_and_b32_e32 v123, 0xffff0000, v185
	v_add_f32_e32 v118, v118, v122
	v_fmac_f32_e32 v191, v117, v117
	v_add_f32_e32 v119, v119, v123
	v_fmac_f32_e32 v191, v118, v118
	v_add_f32_e32 v120, v112, v124
	v_fmac_f32_e32 v191, v119, v119
	v_lshlrev_b32_e32 v126, 16, v187
	v_add_f32_e32 v121, v113, v125
	v_fmac_f32_e32 v191, v120, v120
	v_and_b32_e32 v127, 0xffff0000, v187
	v_add_f32_e32 v122, v114, v126
	v_fmac_f32_e32 v191, v121, v121
	v_add_f32_e32 v115, v115, v127
	v_fmac_f32_e32 v191, v122, v122
	v_cvt_pk_bf16_f32 v112, v116, v117
	v_cvt_pk_bf16_f32 v113, v118, v119
	v_fmac_f32_e32 v191, v115, v115
	v_cvt_pk_bf16_f32 v114, v120, v121
	v_cvt_pk_bf16_f32 v115, v122, v115
	flat_store_dwordx4 v[230:231], v[112:115] offset:256 sc1
	s_nop 1
	v_and_b32_e32 v113, 64, v238
	v_xor_b32_e32 v112, 16, v238
	v_add_u32_e32 v113, 64, v113
	v_cmp_lt_i32_e32 vcc, v112, v113
	v_xor_b32_e32 v115, 32, v238
	s_nop 0
	v_cndmask_b32_e32 v112, v238, v112, vcc
	v_lshlrev_b32_e32 v112, 2, v112
	ds_bpermute_b32 v114, v112, v191
	v_cmp_lt_i32_e32 vcc, v115, v113
	s_waitcnt lgkmcnt(0)
	v_add_f32_e32 v114, v191, v114
	v_cndmask_b32_e32 v113, v238, v115, vcc
	v_lshlrev_b32_e32 v113, 2, v113
	ds_bpermute_b32 v115, v113, v114
	s_and_saveexec_b64 s[14:15], s[4:5]
	s_cbranch_execz .LBB0_122
	s_waitcnt lgkmcnt(0)
	v_add_f32_e32 v114, v114, v115
	v_mul_f32_e32 v114, 0x49800000, v114
	v_trunc_f32_e32 v114, v114
	v_mul_f32_e32 v115, 0x2f800000, v114
	v_floor_f32_e32 v115, v115
	v_fmac_f32_e32 v114, 0xcf800000, v115
	v_cvt_u32_f32_e32 v114, v114
	v_cvt_u32_f32_e32 v115, v115
	v_readlane_b32 s16, v254, 37
	v_readlane_b32 s17, v254, 38
	s_nop 1
	v_lshl_add_u64 v[116:117], v[228:229], 3, s[16:17]
	flat_atomic_add_x2 v[116:117], v[114:115]
; __device__ __forceinline__ void unpack8(u32x4 w, float* f) { f[0] = bflo(w.x); f[1] = bfhi(w.x); f[2] = bflo(w.y); f[3] = bfhi(w.y); f[4] = bflo(w.z); f[5] = bfhi(w.z); f[6] = bflo(w.w); f[7] = bfhi(w.w); }
; __device__ __forceinline__ u32x4 pack8(const float* f) { u32x4 w; w.x = cvt_pk_bf16(f[0], f[1]); w.y = cvt_pk_bf16(f[2], f[3]); w.z = cvt_pk_bf16(f[4], f[5]); w.w = cvt_pk_bf16(f[6], f[7]); return w; }
;     __device__ __forceinline__ void operator()(const f32x4 (&acc)[2][2][4][2], const Unit& u, int wr, int wc, int fr, int fq, LAS unsigned char* lds, int par, int npm, int tid) const {
;     ...
;                 for (int bj = 0; bj < 2; ++bj) old[ai][m][bj] = *(const u32x4*)(Hb + (size_t)(row0 + ai * HALF + m * 16) * ldc + col0 + bj * HALF);
; #pragma unroll
;         for (int ai = 0; ai < 2; ++ai)
; #pragma unroll
;             for (int m = 0; m < 4; ++m) { const int row = row0 + ai * HALF + m * 16; bf16_t* hp = Hb + (size_t)row * ldc + col0;
;                 float part = 0.f;
; #pragma unroll
;                 for (int bj = 0; bj < 2; ++bj) { float o[8]; unpack8(old[ai][m][bj], o);
;                     const f32x4 a0 = acc[ai][bj][m][0], a1 = acc[ai][bj][m][1];
;                     float v[8] = {o[0] + a0[0], o[1] + a0[1], o[2] + a0[2], o[3] + a0[3], o[4] + a1[0], o[5] + a1[1], o[6] + a1[2], o[7] + a1[3]};
; #pragma unroll
;                     for (int k = 0; k < 8; ++k) part += v[k] * v[k];
;                     *(u32x4*)(hp + bj * HALF) = pack8(v); }
;                 part += __shfl_xor(part, 16); part += __shfl_xor(part, 32);
;                 if (fq == 0) atomicAdd(ssq + row, (unsigned long long)(part * 1048576.f)); }
.LBB0_122:
	s_or_b64 exec, exec, s[14:15]
	v_and_b32_e32 v117, 0xffff0000, v180
	v_lshlrev_b32_e32 v116, 16, v180
	v_and_b32_e32 v119, 0xffff0000, v181
	v_add_f32_e32 v109, v109, v117
	v_lshlrev_b32_e32 v118, 16, v181
	v_add_f32_e32 v108, v108, v116
	v_add_f32_e32 v111, v111, v119
	v_mul_f32_e32 v119, v109, v109
	v_add_f32_e32 v110, v110, v118
	v_fmac_f32_e32 v119, v108, v108
	v_lshlrev_b32_e32 v120, 16, v182
	v_fmac_f32_e32 v119, v110, v110
	v_and_b32_e32 v121, 0xffff0000, v182
	v_add_f32_e32 v116, v104, v120
	v_fmac_f32_e32 v119, v111, v111
	v_lshlrev_b32_e32 v122, 16, v183
	v_add_f32_e32 v117, v105, v121
	v_fmac_f32_e32 v119, v116, v116
	v_and_b32_e32 v123, 0xffff0000, v183
	v_add_f32_e32 v118, v106, v122
	v_fmac_f32_e32 v119, v117, v117
	v_add_f32_e32 v107, v107, v123
	v_fmac_f32_e32 v119, v118, v118
	v_lshlrev_b32_e32 v106, 16, v176
	v_fmac_f32_e32 v119, v107, v107
	v_cvt_pk_bf16_f32 v104, v108, v109
	v_and_b32_e32 v108, 0xffff0000, v176
	v_add_f32_e32 v100, v100, v106
	v_lshlrev_b32_e32 v109, 16, v177
	v_add_f32_e32 v101, v101, v108
	v_fmac_f32_e32 v119, v100, v100
	v_cvt_pk_bf16_f32 v105, v110, v111
	v_and_b32_e32 v110, 0xffff0000, v177
	v_add_f32_e32 v102, v102, v109
	v_fmac_f32_e32 v119, v101, v101
	v_lshlrev_b32_e32 v111, 16, v178
	v_add_f32_e32 v103, v103, v110
	v_fmac_f32_e32 v119, v102, v102
	v_and_b32_e32 v120, 0xffff0000, v178
	v_add_f32_e32 v108, v96, v111
	v_fmac_f32_e32 v119, v103, v103
	v_lshlrev_b32_e32 v121, 16, v179
	v_add_f32_e32 v109, v97, v120
	v_fmac_f32_e32 v119, v108, v108
	v_and_b32_e32 v122, 0xffff0000, v179
	v_add_f32_e32 v110, v98, v121
	v_fmac_f32_e32 v119, v109, v109
	v_add_f32_e32 v111, v99, v122
	v_fmac_f32_e32 v119, v110, v110
	v_fmac_f32_e32 v119, v111, v111
	ds_bpermute_b32 v96, v112, v119
	v_readlane_b32 s14, v254, 8
	s_waitcnt lgkmcnt(0)
	v_lshlrev_b64 v[114:115], 11, v[226:227]
	v_readlane_b32 s15, v254, 9
	v_cvt_pk_bf16_f32 v106, v116, v117
	v_add_f32_e32 v96, v119, v96
	ds_bpermute_b32 v97, v113, v96
	v_lshl_add_u64 v[114:115], v[114:115], 1, s[14:15]
	v_lshl_add_u64 v[114:115], v[212:213], 1, v[114:115]
	v_cvt_pk_bf16_f32 v107, v118, v107
	flat_store_dwordx4 v[114:115], v[104:107] sc1
	v_cvt_pk_bf16_f32 v98, v100, v101
	v_cvt_pk_bf16_f32 v99, v102, v103
	v_cvt_pk_bf16_f32 v100, v108, v109
	v_cvt_pk_bf16_f32 v101, v110, v111
	flat_store_dwordx4 v[114:115], v[98:101] offset:256 sc1
	s_and_saveexec_b64 s[14:15], s[4:5]
	s_cbranch_execz .LBB0_124
	s_waitcnt lgkmcnt(0)
	v_add_f32_e32 v96, v96, v97
	v_mul_f32_e32 v96, 0x49800000, v96
	v_trunc_f32_e32 v96, v96
	v_mul_f32_e32 v97, 0x2f800000, v96
	v_floor_f32_e32 v97, v97
	v_fmac_f32_e32 v96, 0xcf800000, v97
	v_cvt_u32_f32_e32 v96, v96
	v_cvt_u32_f32_e32 v97, v97
	v_readlane_b32 s16, v254, 37
	v_readlane_b32 s17, v254, 38
	s_nop 1
	v_lshl_add_u64 v[98:99], v[226:227], 3, s[16:17]
	flat_atomic_add_x2 v[98:99], v[96:97]
.LBB0_124:
	s_or_b64 exec, exec, s[14:15]
	v_and_b32_e32 v99, 0xffff0000, v172
	v_lshlrev_b32_e32 v98, 16, v172
	v_and_b32_e32 v101, 0xffff0000, v173
	v_add_f32_e32 v93, v93, v99
	v_lshlrev_b32_e32 v100, 16, v173
	v_add_f32_e32 v92, v92, v98
	v_add_f32_e32 v95, v95, v101
	v_mul_f32_e32 v101, v93, v93
	v_add_f32_e32 v94, v94, v100
	v_fmac_f32_e32 v101, v92, v92
	v_lshlrev_b32_e32 v102, 16, v174
	v_fmac_f32_e32 v101, v94, v94
	v_and_b32_e32 v103, 0xffff0000, v174
	v_add_f32_e32 v98, v88, v102
	v_fmac_f32_e32 v101, v95, v95
	v_lshlrev_b32_e32 v104, 16, v175
	v_add_f32_e32 v99, v89, v103
	v_fmac_f32_e32 v101, v98, v98
	v_and_b32_e32 v105, 0xffff0000, v175
	v_add_f32_e32 v100, v90, v104
	v_fmac_f32_e32 v101, v99, v99
	v_add_f32_e32 v91, v91, v105
	v_fmac_f32_e32 v101, v100, v100
	v_lshlrev_b32_e32 v90, 16, v168
	v_fmac_f32_e32 v101, v91, v91
	v_cvt_pk_bf16_f32 v88, v92, v93
	v_and_b32_e32 v92, 0xffff0000, v168
	v_add_f32_e32 v84, v84, v90
	v_lshlrev_b32_e32 v93, 16, v169
	v_add_f32_e32 v85, v85, v92
	v_fmac_f32_e32 v101, v84, v84
	v_cvt_pk_bf16_f32 v89, v94, v95
	v_and_b32_e32 v94, 0xffff0000, v169
	v_add_f32_e32 v86, v86, v93
	v_fmac_f32_e32 v101, v85, v85
	v_lshlrev_b32_e32 v95, 16, v170
	v_add_f32_e32 v87, v87, v94
	v_fmac_f32_e32 v101, v86, v86
	v_and_b32_e32 v102, 0xffff0000, v170
	v_add_f32_e32 v92, v80, v95
	v_fmac_f32_e32 v101, v87, v87
	v_lshlrev_b32_e32 v103, 16, v171
	v_add_f32_e32 v93, v81, v102
	v_fmac_f32_e32 v101, v92, v92
	v_and_b32_e32 v104, 0xffff0000, v171
	v_add_f32_e32 v94, v82, v103
	v_fmac_f32_e32 v101, v93, v93
	v_add_f32_e32 v95, v83, v104
	v_fmac_f32_e32 v101, v94, v94
	v_fmac_f32_e32 v101, v95, v95
	ds_bpermute_b32 v80, v112, v101
	v_readlane_b32 s14, v254, 8
	s_waitcnt lgkmcnt(0)
	v_lshlrev_b64 v[96:97], 11, v[224:225]
	v_readlane_b32 s15, v254, 9
	v_cvt_pk_bf16_f32 v90, v98, v99
	v_add_f32_e32 v80, v101, v80
	ds_bpermute_b32 v81, v113, v80
	v_lshl_add_u64 v[96:97], v[96:97], 1, s[14:15]
	v_lshl_add_u64 v[96:97], v[212:213], 1, v[96:97]
	v_cvt_pk_bf16_f32 v91, v100, v91
	flat_store_dwordx4 v[96:97], v[88:91] sc1
	v_cvt_pk_bf16_f32 v82, v84, v85
	v_cvt_pk_bf16_f32 v83, v86, v87
	v_cvt_pk_bf16_f32 v84, v92, v93
	v_cvt_pk_bf16_f32 v85, v94, v95
	flat_store_dwordx4 v[96:97], v[82:85] offset:256 sc1
	s_and_saveexec_b64 s[14:15], s[4:5]
	s_cbranch_execz .LBB0_126
	s_waitcnt lgkmcnt(0)
	v_add_f32_e32 v80, v80, v81
	v_mul_f32_e32 v80, 0x49800000, v80
	v_trunc_f32_e32 v80, v80
	v_mul_f32_e32 v81, 0x2f800000, v80
	v_floor_f32_e32 v81, v81
	v_fmac_f32_e32 v80, 0xcf800000, v81
	v_cvt_u32_f32_e32 v80, v80
	v_cvt_u32_f32_e32 v81, v81
	v_readlane_b32 s16, v254, 37
	v_readlane_b32 s17, v254, 38
	s_nop 1
	v_lshl_add_u64 v[82:83], v[224:225], 3, s[16:17]
	flat_atomic_add_x2 v[82:83], v[80:81]
; __device__ __forceinline__ void unpack8(u32x4 w, float* f) { f[0] = bflo(w.x); f[1] = bfhi(w.x); f[2] = bflo(w.y); f[3] = bfhi(w.y); f[4] = bflo(w.z); f[5] = bfhi(w.z); f[6] = bflo(w.w); f[7] = bfhi(w.w); }
; __device__ __forceinline__ u32x4 pack8(const float* f) { u32x4 w; w.x = cvt_pk_bf16(f[0], f[1]); w.y = cvt_pk_bf16(f[2], f[3]); w.z = cvt_pk_bf16(f[4], f[5]); w.w = cvt_pk_bf16(f[6], f[7]); return w; }
;     __device__ __forceinline__ void operator()(const f32x4 (&acc)[2][2][4][2], const Unit& u, int wr, int wc, int fr, int fq, LAS unsigned char* lds, int par, int npm, int tid) const {
;     ...
;                 for (int bj = 0; bj < 2; ++bj) old[ai][m][bj] = *(const u32x4*)(Hb + (size_t)(row0 + ai * HALF + m * 16) * ldc + col0 + bj * HALF);
; #pragma unroll
;         for (int ai = 0; ai < 2; ++ai)
; #pragma unroll
;             for (int m = 0; m < 4; ++m) { const int row = row0 + ai * HALF + m * 16; bf16_t* hp = Hb + (size_t)row * ldc + col0;
;                 float part = 0.f;
; #pragma unroll
;                 for (int bj = 0; bj < 2; ++bj) { float o[8]; unpack8(old[ai][m][bj], o);
;                     const f32x4 a0 = acc[ai][bj][m][0], a1 = acc[ai][bj][m][1];
;                     float v[8] = {o[0] + a0[0], o[1] + a0[1], o[2] + a0[2], o[3] + a0[3], o[4] + a1[0], o[5] + a1[1], o[6] + a1[2], o[7] + a1[3]};
; #pragma unroll
;                     for (int k = 0; k < 8; ++k) part += v[k] * v[k];
;                     *(u32x4*)(hp + bj * HALF) = pack8(v); }
;                 part += __shfl_xor(part, 16); part += __shfl_xor(part, 32);
;                 if (fq == 0) atomicAdd(ssq + row, (unsigned long long)(part * 1048576.f)); }
.LBB0_126:
	s_or_b64 exec, exec, s[14:15]
	v_and_b32_e32 v83, 0xffff0000, v164
	v_lshlrev_b32_e32 v82, 16, v164
	v_and_b32_e32 v85, 0xffff0000, v165
	v_add_f32_e32 v77, v77, v83
	v_lshlrev_b32_e32 v84, 16, v165
	v_add_f32_e32 v76, v76, v82
	v_add_f32_e32 v79, v79, v85
	v_mul_f32_e32 v85, v77, v77
	v_add_f32_e32 v78, v78, v84
	v_fmac_f32_e32 v85, v76, v76
	v_lshlrev_b32_e32 v86, 16, v166
	v_fmac_f32_e32 v85, v78, v78
	v_and_b32_e32 v87, 0xffff0000, v166
	v_add_f32_e32 v82, v72, v86
	v_fmac_f32_e32 v85, v79, v79
	v_lshlrev_b32_e32 v88, 16, v167
	v_add_f32_e32 v83, v73, v87
	v_fmac_f32_e32 v85, v82, v82
	v_and_b32_e32 v89, 0xffff0000, v167
	v_add_f32_e32 v84, v74, v88
	v_fmac_f32_e32 v85, v83, v83
	v_add_f32_e32 v75, v75, v89
	v_fmac_f32_e32 v85, v84, v84
	v_lshlrev_b32_e32 v74, 16, v160
	v_fmac_f32_e32 v85, v75, v75
	v_cvt_pk_bf16_f32 v72, v76, v77
	v_and_b32_e32 v76, 0xffff0000, v160
	v_add_f32_e32 v68, v68, v74
	v_lshlrev_b32_e32 v77, 16, v161
	v_add_f32_e32 v69, v69, v76
	v_fmac_f32_e32 v85, v68, v68
	v_cvt_pk_bf16_f32 v73, v78, v79
	v_and_b32_e32 v78, 0xffff0000, v161
	v_add_f32_e32 v70, v70, v77
	v_fmac_f32_e32 v85, v69, v69
	v_lshlrev_b32_e32 v79, 16, v162
	v_add_f32_e32 v71, v71, v78
	v_fmac_f32_e32 v85, v70, v70
	v_and_b32_e32 v86, 0xffff0000, v162
	v_add_f32_e32 v76, v64, v79
	v_fmac_f32_e32 v85, v71, v71
	v_lshlrev_b32_e32 v87, 16, v163
	v_add_f32_e32 v77, v65, v86
	v_fmac_f32_e32 v85, v76, v76
	v_and_b32_e32 v88, 0xffff0000, v163
	v_add_f32_e32 v78, v66, v87
	v_fmac_f32_e32 v85, v77, v77
	v_add_f32_e32 v79, v67, v88
	v_fmac_f32_e32 v85, v78, v78
	v_fmac_f32_e32 v85, v79, v79
	ds_bpermute_b32 v64, v112, v85
	v_readlane_b32 s14, v254, 8
	s_waitcnt lgkmcnt(0)
	v_lshlrev_b64 v[80:81], 11, v[222:223]
	v_readlane_b32 s15, v254, 9
	v_cvt_pk_bf16_f32 v74, v82, v83
	v_add_f32_e32 v64, v85, v64
	ds_bpermute_b32 v65, v113, v64
	v_lshl_add_u64 v[80:81], v[80:81], 1, s[14:15]
	v_lshl_add_u64 v[80:81], v[212:213], 1, v[80:81]
	v_cvt_pk_bf16_f32 v75, v84, v75
	flat_store_dwordx4 v[80:81], v[72:75] sc1
	v_cvt_pk_bf16_f32 v66, v68, v69
	v_cvt_pk_bf16_f32 v67, v70, v71
	v_cvt_pk_bf16_f32 v68, v76, v77
	v_cvt_pk_bf16_f32 v69, v78, v79
	flat_store_dwordx4 v[80:81], v[66:69] offset:256 sc1
	s_and_saveexec_b64 s[14:15], s[4:5]
	s_cbranch_execz .LBB0_128
	s_waitcnt lgkmcnt(0)
	v_add_f32_e32 v64, v64, v65
	v_mul_f32_e32 v64, 0x49800000, v64
	v_trunc_f32_e32 v64, v64
	v_mul_f32_e32 v65, 0x2f800000, v64
	v_floor_f32_e32 v65, v65
	v_fmac_f32_e32 v64, 0xcf800000, v65
	v_cvt_u32_f32_e32 v64, v64
	v_cvt_u32_f32_e32 v65, v65
	v_readlane_b32 s16, v254, 37
	v_readlane_b32 s17, v254, 38
	s_nop 1
	v_lshl_add_u64 v[66:67], v[222:223], 3, s[16:17]
	flat_atomic_add_x2 v[66:67], v[64:65]
.LBB0_128:
	s_or_b64 exec, exec, s[14:15]
	v_and_b32_e32 v67, 0xffff0000, v156
	v_lshlrev_b32_e32 v66, 16, v156
	v_and_b32_e32 v69, 0xffff0000, v157
	v_add_f32_e32 v61, v61, v67
	v_lshlrev_b32_e32 v68, 16, v157
	v_add_f32_e32 v60, v60, v66
	v_add_f32_e32 v63, v63, v69
	v_mul_f32_e32 v69, v61, v61
	v_add_f32_e32 v62, v62, v68
	v_fmac_f32_e32 v69, v60, v60
	v_lshlrev_b32_e32 v70, 16, v158
	v_fmac_f32_e32 v69, v62, v62
	v_and_b32_e32 v71, 0xffff0000, v158
	v_add_f32_e32 v66, v56, v70
	v_fmac_f32_e32 v69, v63, v63
	v_lshlrev_b32_e32 v72, 16, v159
	v_add_f32_e32 v67, v57, v71
	v_fmac_f32_e32 v69, v66, v66
	v_and_b32_e32 v73, 0xffff0000, v159
	v_add_f32_e32 v68, v58, v72
	v_fmac_f32_e32 v69, v67, v67
	v_add_f32_e32 v59, v59, v73
	v_fmac_f32_e32 v69, v68, v68
	v_lshlrev_b32_e32 v58, 16, v152
	v_fmac_f32_e32 v69, v59, v59
	v_cvt_pk_bf16_f32 v56, v60, v61
	v_and_b32_e32 v60, 0xffff0000, v152
	v_add_f32_e32 v52, v52, v58
	v_lshlrev_b32_e32 v61, 16, v153
	v_add_f32_e32 v53, v53, v60
	v_fmac_f32_e32 v69, v52, v52
	v_cvt_pk_bf16_f32 v57, v62, v63
	v_and_b32_e32 v62, 0xffff0000, v153
	v_add_f32_e32 v54, v54, v61
	v_fmac_f32_e32 v69, v53, v53
	v_lshlrev_b32_e32 v63, 16, v154
	v_add_f32_e32 v55, v55, v62
	v_fmac_f32_e32 v69, v54, v54
	v_and_b32_e32 v70, 0xffff0000, v154
	v_add_f32_e32 v60, v48, v63
	v_fmac_f32_e32 v69, v55, v55
	v_lshlrev_b32_e32 v71, 16, v155
	v_add_f32_e32 v61, v49, v70
	v_fmac_f32_e32 v69, v60, v60
	v_and_b32_e32 v72, 0xffff0000, v155
	v_add_f32_e32 v62, v50, v71
	v_fmac_f32_e32 v69, v61, v61
	v_add_f32_e32 v63, v51, v72
	v_fmac_f32_e32 v69, v62, v62
	v_fmac_f32_e32 v69, v63, v63
	ds_bpermute_b32 v48, v112, v69
	v_readlane_b32 s14, v254, 8
	s_waitcnt lgkmcnt(0)
	v_lshlrev_b64 v[64:65], 11, v[220:221]
	v_readlane_b32 s15, v254, 9
	v_cvt_pk_bf16_f32 v58, v66, v67
	v_add_f32_e32 v48, v69, v48
	ds_bpermute_b32 v49, v113, v48
	v_lshl_add_u64 v[64:65], v[64:65], 1, s[14:15]
	v_lshl_add_u64 v[64:65], v[212:213], 1, v[64:65]
	v_cvt_pk_bf16_f32 v59, v68, v59
	flat_store_dwordx4 v[64:65], v[56:59] sc1
	v_cvt_pk_bf16_f32 v50, v52, v53
	v_cvt_pk_bf16_f32 v51, v54, v55
	v_cvt_pk_bf16_f32 v52, v60, v61
	v_cvt_pk_bf16_f32 v53, v62, v63
	flat_store_dwordx4 v[64:65], v[50:53] offset:256 sc1
	s_and_saveexec_b64 s[14:15], s[4:5]
	s_cbranch_execz .LBB0_130
	s_waitcnt lgkmcnt(0)
	v_add_f32_e32 v48, v48, v49
	v_mul_f32_e32 v48, 0x49800000, v48
	v_trunc_f32_e32 v48, v48
	v_mul_f32_e32 v49, 0x2f800000, v48
	v_floor_f32_e32 v49, v49
	v_fmac_f32_e32 v48, 0xcf800000, v49
	v_cvt_u32_f32_e32 v48, v48
	v_cvt_u32_f32_e32 v49, v49
	v_readlane_b32 s16, v254, 37
	v_readlane_b32 s17, v254, 38
	s_nop 1
	v_lshl_add_u64 v[50:51], v[220:221], 3, s[16:17]
	flat_atomic_add_x2 v[50:51], v[48:49]
; __device__ __forceinline__ void unpack8(u32x4 w, float* f) { f[0] = bflo(w.x); f[1] = bfhi(w.x); f[2] = bflo(w.y); f[3] = bfhi(w.y); f[4] = bflo(w.z); f[5] = bfhi(w.z); f[6] = bflo(w.w); f[7] = bfhi(w.w); }
; __device__ __forceinline__ u32x4 pack8(const float* f) { u32x4 w; w.x = cvt_pk_bf16(f[0], f[1]); w.y = cvt_pk_bf16(f[2], f[3]); w.z = cvt_pk_bf16(f[4], f[5]); w.w = cvt_pk_bf16(f[6], f[7]); return w; }
;     __device__ __forceinline__ void operator()(const f32x4 (&acc)[2][2][4][2], const Unit& u, int wr, int wc, int fr, int fq, LAS unsigned char* lds, int par, int npm, int tid) const {
;     ...
;                 for (int bj = 0; bj < 2; ++bj) old[ai][m][bj] = *(const u32x4*)(Hb + (size_t)(row0 + ai * HALF + m * 16) * ldc + col0 + bj * HALF);
; #pragma unroll
;         for (int ai = 0; ai < 2; ++ai)
; #pragma unroll
;             for (int m = 0; m < 4; ++m) { const int row = row0 + ai * HALF + m * 16; bf16_t* hp = Hb + (size_t)row * ldc + col0;
;                 float part = 0.f;
; #pragma unroll
;                 for (int bj = 0; bj < 2; ++bj) { float o[8]; unpack8(old[ai][m][bj], o);
;                     const f32x4 a0 = acc[ai][bj][m][0], a1 = acc[ai][bj][m][1];
;                     float v[8] = {o[0] + a0[0], o[1] + a0[1], o[2] + a0[2], o[3] + a0[3], o[4] + a1[0], o[5] + a1[1], o[6] + a1[2], o[7] + a1[3]};
; #pragma unroll
;                     for (int k = 0; k < 8; ++k) part += v[k] * v[k];
;                     *(u32x4*)(hp + bj * HALF) = pack8(v); }
;                 part += __shfl_xor(part, 16); part += __shfl_xor(part, 32);
;                 if (fq == 0) atomicAdd(ssq + row, (unsigned long long)(part * 1048576.f)); }
.LBB0_130:
	s_or_b64 exec, exec, s[14:15]
	v_and_b32_e32 v51, 0xffff0000, v148
	v_lshlrev_b32_e32 v50, 16, v148
	v_and_b32_e32 v53, 0xffff0000, v149
	v_add_f32_e32 v45, v45, v51
	v_lshlrev_b32_e32 v52, 16, v149
	v_add_f32_e32 v44, v44, v50
	v_add_f32_e32 v47, v47, v53
	v_mul_f32_e32 v53, v45, v45
	v_add_f32_e32 v46, v46, v52
	v_fmac_f32_e32 v53, v44, v44
	v_lshlrev_b32_e32 v54, 16, v150
	v_fmac_f32_e32 v53, v46, v46
	v_and_b32_e32 v55, 0xffff0000, v150
	v_add_f32_e32 v50, v40, v54
	v_fmac_f32_e32 v53, v47, v47
	v_lshlrev_b32_e32 v56, 16, v151
	v_add_f32_e32 v51, v41, v55
	v_fmac_f32_e32 v53, v50, v50
	v_and_b32_e32 v57, 0xffff0000, v151
	v_add_f32_e32 v52, v42, v56
	v_fmac_f32_e32 v53, v51, v51
	v_add_f32_e32 v43, v43, v57
	v_fmac_f32_e32 v53, v52, v52
	v_lshlrev_b32_e32 v42, 16, v144
	v_fmac_f32_e32 v53, v43, v43
	v_cvt_pk_bf16_f32 v40, v44, v45
	v_and_b32_e32 v44, 0xffff0000, v144
	v_add_f32_e32 v36, v36, v42
	v_lshlrev_b32_e32 v45, 16, v145
	v_add_f32_e32 v37, v37, v44
	v_fmac_f32_e32 v53, v36, v36
	v_cvt_pk_bf16_f32 v41, v46, v47
	v_and_b32_e32 v46, 0xffff0000, v145
	v_add_f32_e32 v38, v38, v45
	v_fmac_f32_e32 v53, v37, v37
	v_lshlrev_b32_e32 v47, 16, v146
	v_add_f32_e32 v39, v39, v46
	v_fmac_f32_e32 v53, v38, v38
	v_and_b32_e32 v54, 0xffff0000, v146
	v_add_f32_e32 v44, v32, v47
	v_fmac_f32_e32 v53, v39, v39
	v_lshlrev_b32_e32 v55, 16, v147
	v_add_f32_e32 v45, v33, v54
	v_fmac_f32_e32 v53, v44, v44
	v_and_b32_e32 v56, 0xffff0000, v147
	v_add_f32_e32 v46, v34, v55
	v_fmac_f32_e32 v53, v45, v45
	v_add_f32_e32 v47, v35, v56
	v_fmac_f32_e32 v53, v46, v46
	v_fmac_f32_e32 v53, v47, v47
	ds_bpermute_b32 v32, v112, v53
	v_readlane_b32 s14, v254, 8
	s_waitcnt lgkmcnt(0)
	v_lshlrev_b64 v[48:49], 11, v[218:219]
	v_readlane_b32 s15, v254, 9
	v_cvt_pk_bf16_f32 v42, v50, v51
	v_add_f32_e32 v32, v53, v32
	ds_bpermute_b32 v33, v113, v32
	v_lshl_add_u64 v[48:49], v[48:49], 1, s[14:15]
	v_lshl_add_u64 v[48:49], v[212:213], 1, v[48:49]
	v_cvt_pk_bf16_f32 v43, v52, v43
	flat_store_dwordx4 v[48:49], v[40:43] sc1
	v_cvt_pk_bf16_f32 v34, v36, v37
	v_cvt_pk_bf16_f32 v35, v38, v39
	v_cvt_pk_bf16_f32 v36, v44, v45
	v_cvt_pk_bf16_f32 v37, v46, v47
	flat_store_dwordx4 v[48:49], v[34:37] offset:256 sc1
	s_and_saveexec_b64 s[14:15], s[4:5]
	s_cbranch_execz .LBB0_132
	s_waitcnt lgkmcnt(0)
	v_add_f32_e32 v32, v32, v33
	v_mul_f32_e32 v32, 0x49800000, v32
	v_trunc_f32_e32 v32, v32
	v_mul_f32_e32 v33, 0x2f800000, v32
	v_floor_f32_e32 v33, v33
	v_fmac_f32_e32 v32, 0xcf800000, v33
	v_cvt_u32_f32_e32 v32, v32
	v_cvt_u32_f32_e32 v33, v33
	v_readlane_b32 s16, v254, 37
	v_readlane_b32 s17, v254, 38
	s_nop 1
	v_lshl_add_u64 v[34:35], v[218:219], 3, s[16:17]
	flat_atomic_add_x2 v[34:35], v[32:33]
; __device__ __forceinline__ void unpack8(u32x4 w, float* f) { f[0] = bflo(w.x); f[1] = bfhi(w.x); f[2] = bflo(w.y); f[3] = bfhi(w.y); f[4] = bflo(w.z); f[5] = bfhi(w.z); f[6] = bflo(w.w); f[7] = bfhi(w.w); }
; __device__ __forceinline__ u32x4 pack8(const float* f) { u32x4 w; w.x = cvt_pk_bf16(f[0], f[1]); w.y = cvt_pk_bf16(f[2], f[3]); w.z = cvt_pk_bf16(f[4], f[5]); w.w = cvt_pk_bf16(f[6], f[7]); return w; }
;     __device__ __forceinline__ void operator()(const f32x4 (&acc)[2][2][4][2], const Unit& u, int wr, int wc, int fr, int fq, LAS unsigned char* lds, int par, int npm, int tid) const {
;     ...
;                 for (int bj = 0; bj < 2; ++bj) old[ai][m][bj] = *(const u32x4*)(Hb + (size_t)(row0 + ai * HALF + m * 16) * ldc + col0 + bj * HALF);
; #pragma unroll
;         for (int ai = 0; ai < 2; ++ai)
; #pragma unroll
;             for (int m = 0; m < 4; ++m) { const int row = row0 + ai * HALF + m * 16; bf16_t* hp = Hb + (size_t)row * ldc + col0;
;                 float part = 0.f;
; #pragma unroll
;                 for (int bj = 0; bj < 2; ++bj) { float o[8]; unpack8(old[ai][m][bj], o);
;                     const f32x4 a0 = acc[ai][bj][m][0], a1 = acc[ai][bj][m][1];
;                     float v[8] = {o[0] + a0[0], o[1] + a0[1], o[2] + a0[2], o[3] + a0[3], o[4] + a1[0], o[5] + a1[1], o[6] + a1[2], o[7] + a1[3]};
; #pragma unroll
;                     for (int k = 0; k < 8; ++k) part += v[k] * v[k];
;                     *(u32x4*)(hp + bj * HALF) = pack8(v); }
;                 part += __shfl_xor(part, 16); part += __shfl_xor(part, 32);
;                 if (fq == 0) atomicAdd(ssq + row, (unsigned long long)(part * 1048576.f)); }
.LBB0_132:
	s_or_b64 exec, exec, s[14:15]
	v_and_b32_e32 v35, 0xffff0000, v136
	v_lshlrev_b32_e32 v34, 16, v136
	v_and_b32_e32 v37, 0xffff0000, v137
	v_add_f32_e32 v29, v29, v35
	v_lshlrev_b32_e32 v36, 16, v137
	v_add_f32_e32 v28, v28, v34
	v_add_f32_e32 v31, v31, v37
	v_mul_f32_e32 v37, v29, v29
	v_add_f32_e32 v30, v30, v36
	v_fmac_f32_e32 v37, v28, v28
	v_lshlrev_b32_e32 v38, 16, v138
	v_fmac_f32_e32 v37, v30, v30
	v_and_b32_e32 v39, 0xffff0000, v138
	v_add_f32_e32 v34, v24, v38
	v_fmac_f32_e32 v37, v31, v31
	v_lshlrev_b32_e32 v40, 16, v139
	v_add_f32_e32 v35, v25, v39
	v_fmac_f32_e32 v37, v34, v34
	v_and_b32_e32 v41, 0xffff0000, v139
	v_add_f32_e32 v36, v26, v40
	v_fmac_f32_e32 v37, v35, v35
	v_add_f32_e32 v27, v27, v41
	v_fmac_f32_e32 v37, v36, v36
	v_lshlrev_b32_e32 v26, 16, v128
	v_fmac_f32_e32 v37, v27, v27
	v_cvt_pk_bf16_f32 v24, v28, v29
	v_and_b32_e32 v28, 0xffff0000, v128
	v_add_f32_e32 v20, v20, v26
	v_lshlrev_b32_e32 v29, 16, v129
	v_add_f32_e32 v21, v21, v28
	v_fmac_f32_e32 v37, v20, v20
	v_cvt_pk_bf16_f32 v25, v30, v31
	v_and_b32_e32 v30, 0xffff0000, v129
	v_add_f32_e32 v22, v22, v29
	v_fmac_f32_e32 v37, v21, v21
	v_lshlrev_b32_e32 v31, 16, v130
	v_add_f32_e32 v23, v23, v30
	v_fmac_f32_e32 v37, v22, v22
	v_and_b32_e32 v38, 0xffff0000, v130
	v_add_f32_e32 v28, v16, v31
	v_fmac_f32_e32 v37, v23, v23
	v_lshlrev_b32_e32 v39, 16, v131
	v_add_f32_e32 v29, v17, v38
	v_fmac_f32_e32 v37, v28, v28
	v_and_b32_e32 v40, 0xffff0000, v131
	v_add_f32_e32 v30, v18, v39
	v_fmac_f32_e32 v37, v29, v29
	v_add_f32_e32 v31, v19, v40
	v_fmac_f32_e32 v37, v30, v30
	v_fmac_f32_e32 v37, v31, v31
	ds_bpermute_b32 v16, v112, v37
	v_readlane_b32 s14, v254, 8
	s_waitcnt lgkmcnt(0)
	v_lshlrev_b64 v[32:33], 11, v[216:217]
	v_readlane_b32 s15, v254, 9
	v_cvt_pk_bf16_f32 v26, v34, v35
	v_add_f32_e32 v16, v37, v16
	ds_bpermute_b32 v17, v113, v16
	v_lshl_add_u64 v[32:33], v[32:33], 1, s[14:15]
	v_lshl_add_u64 v[32:33], v[212:213], 1, v[32:33]
	v_cvt_pk_bf16_f32 v27, v36, v27
	flat_store_dwordx4 v[32:33], v[24:27] sc1
	v_cvt_pk_bf16_f32 v18, v20, v21
	v_cvt_pk_bf16_f32 v19, v22, v23
	v_cvt_pk_bf16_f32 v20, v28, v29
	v_cvt_pk_bf16_f32 v21, v30, v31
	flat_store_dwordx4 v[32:33], v[18:21] offset:256 sc1
	s_and_saveexec_b64 s[14:15], s[4:5]
	s_cbranch_execz .LBB0_134
	s_waitcnt lgkmcnt(0)
	v_add_f32_e32 v16, v16, v17
	v_mul_f32_e32 v16, 0x49800000, v16
	v_trunc_f32_e32 v16, v16
	v_mul_f32_e32 v17, 0x2f800000, v16
	v_floor_f32_e32 v17, v17
	v_fmac_f32_e32 v16, 0xcf800000, v17
	v_cvt_u32_f32_e32 v16, v16
	v_cvt_u32_f32_e32 v17, v17
	v_readlane_b32 s16, v254, 37
	v_readlane_b32 s17, v254, 38
	s_nop 1
	v_lshl_add_u64 v[18:19], v[216:217], 3, s[16:17]
	flat_atomic_add_x2 v[18:19], v[16:17]
.LBB0_134:
	s_or_b64 exec, exec, s[14:15]
	v_and_b32_e32 v19, 0xffff0000, v140
	v_lshlrev_b32_e32 v18, 16, v140
	v_and_b32_e32 v21, 0xffff0000, v141
	v_add_f32_e32 v13, v13, v19
	v_lshlrev_b32_e32 v20, 16, v141
	v_add_f32_e32 v12, v12, v18
	v_add_f32_e32 v15, v15, v21
	v_mul_f32_e32 v21, v13, v13
	v_add_f32_e32 v14, v14, v20
	v_fmac_f32_e32 v21, v12, v12
	v_lshlrev_b32_e32 v22, 16, v142
	v_fmac_f32_e32 v21, v14, v14
	v_and_b32_e32 v23, 0xffff0000, v142
	v_add_f32_e32 v18, v8, v22
	v_fmac_f32_e32 v21, v15, v15
	v_lshlrev_b32_e32 v24, 16, v143
	v_add_f32_e32 v19, v9, v23
	v_fmac_f32_e32 v21, v18, v18
	v_and_b32_e32 v25, 0xffff0000, v143
	v_add_f32_e32 v20, v10, v24
	v_fmac_f32_e32 v21, v19, v19
	v_add_f32_e32 v11, v11, v25
	v_fmac_f32_e32 v21, v20, v20
	v_lshlrev_b32_e32 v10, 16, v132
	v_fmac_f32_e32 v21, v11, v11
	v_cvt_pk_bf16_f32 v8, v12, v13
	v_and_b32_e32 v12, 0xffff0000, v132
	v_add_f32_e32 v4, v4, v10
	v_lshlrev_b32_e32 v13, 16, v133
	v_add_f32_e32 v5, v5, v12
	v_fmac_f32_e32 v21, v4, v4
	v_cvt_pk_bf16_f32 v9, v14, v15
	v_and_b32_e32 v14, 0xffff0000, v133
	v_add_f32_e32 v6, v6, v13
	v_fmac_f32_e32 v21, v5, v5
	v_lshlrev_b32_e32 v15, 16, v134
	v_add_f32_e32 v7, v7, v14
	v_fmac_f32_e32 v21, v6, v6
	v_and_b32_e32 v22, 0xffff0000, v134
	v_add_f32_e32 v12, v0, v15
	v_fmac_f32_e32 v21, v7, v7
	v_lshlrev_b32_e32 v23, 16, v135
	v_add_f32_e32 v13, v1, v22
	v_fmac_f32_e32 v21, v12, v12
	v_and_b32_e32 v24, 0xffff0000, v135
	v_add_f32_e32 v14, v2, v23
	v_fmac_f32_e32 v21, v13, v13
	v_add_f32_e32 v15, v3, v24
	v_fmac_f32_e32 v21, v14, v14
	v_fmac_f32_e32 v21, v15, v15
	ds_bpermute_b32 v0, v112, v21
	v_readlane_b32 s14, v254, 8
	s_waitcnt lgkmcnt(0)
	v_lshlrev_b64 v[16:17], 11, v[214:215]
	v_readlane_b32 s15, v254, 9
	v_cvt_pk_bf16_f32 v10, v18, v19
	v_add_f32_e32 v0, v21, v0
	ds_bpermute_b32 v1, v113, v0
	v_lshl_add_u64 v[16:17], v[16:17], 1, s[14:15]
	v_lshl_add_u64 v[16:17], v[212:213], 1, v[16:17]
	v_cvt_pk_bf16_f32 v11, v20, v11
	flat_store_dwordx4 v[16:17], v[8:11] sc1
	v_cvt_pk_bf16_f32 v2, v4, v5
	v_cvt_pk_bf16_f32 v3, v6, v7
	v_cvt_pk_bf16_f32 v4, v12, v13
	v_cvt_pk_bf16_f32 v5, v14, v15
	flat_store_dwordx4 v[16:17], v[2:5] offset:256 sc1
	s_and_saveexec_b64 s[14:15], s[4:5]
	s_cbranch_execz .LBB0_105
	s_waitcnt lgkmcnt(0)
	v_add_f32_e32 v0, v0, v1
	v_mul_f32_e32 v0, 0x49800000, v0
	v_trunc_f32_e32 v0, v0
	v_mul_f32_e32 v1, 0x2f800000, v0
	v_floor_f32_e32 v1, v1
	v_fmac_f32_e32 v0, 0xcf800000, v1
	v_cvt_u32_f32_e32 v0, v0
	v_cvt_u32_f32_e32 v1, v1
	v_readlane_b32 s16, v254, 37
	v_readlane_b32 s17, v254, 38
	s_nop 1
	v_lshl_add_u64 v[2:3], v[214:215], 3, s[16:17]
	flat_atomic_add_x2 v[2:3], v[0:1]
	s_branch .LBB0_105

; #define LAS __attribute__((address_space(3)))
; __device__ __forceinline__ unsigned cvt_pk_bf16(float lo, float hi) { unsigned r; asm volatile("v_cvt_pk_bf16_f32 %0, %1, %2" : "=v"(r) : "v"(lo), "v"(hi)); return r; }
;     __device__ __forceinline__ void stash(unsigned long long v, LAS unsigned char* lds, int par, int tid) const { if (tid < 256) *(LAS float*)(lds + 131072 + par * 1024 + tid * 4) = rsqrtf((float)v * (1.f / (1048576.f * DM)) + EPS_); }
;     __device__ __forceinline__ void operator()(const f32x4 (&acc)[2][2][4][2], const Unit& u, int wr, int wc, int fr, int fq, LAS unsigned char* lds, int par, int npm, int tid) const {
;         const int row0 = u.pm * BM + wr * 64 + fr, col0 = u.pn * BM + wc * 32 + 8 * fq;
;         unsigned long long nx = 0ull; if (npm >= 0) nx = prefetch(npm, tid);
; #pragma unroll
;         for (int ai = 0; ai < 2; ++ai)
; #pragma unroll
;             for (int m = 0; m < 4; ++m) { const int row = row0 + ai * HALF + m * 16; bf16_t* rowp = O + (size_t)row * ldc + col0;
;                 const float rstd = *(const LAS float*)(lds + 131072 + par * 1024 + (wr * 64 + fr + ai * HALF + m * 16) * 4);
; #pragma unroll
;                 for (int bj = 0; bj < 2; ++bj) { f32x4 v0 = acc[ai][bj][m][0] * rstd, v1 = acc[ai][bj][m][1] * rstd;
;                     if (ACT == 1) {
; #pragma unroll
;                         for (int j = 0; j < 4; ++j) { const float a = fmaxf(v0[j], 0.f), b = fmaxf(v1[j], 0.f); v0[j] = a * a; v1[j] = b * b; } }
;                     u32x4 w; w.x = cvt_pk_bf16(v0[0], v0[1]); w.y = cvt_pk_bf16(v0[2], v0[3]); w.z = cvt_pk_bf16(v1[0], v1[1]); w.w = cvt_pk_bf16(v1[2], v1[3]);
;                     *(u32x4*)(rowp + bj * HALF) = w; } }
;         if (npm >= 0) stash(nx, lds, par ^ 1, tid);
.LBB0_168:
	s_or_b64 exec, exec, s[16:17]
	s_lshl_b32 s16, s41, 10
	s_and_b32 s18, s16, 0x400
	v_add_u32_e32 v152, s18, v147
	ds_read_b32 v154, v152
	v_lshl_add_u32 v140, s39, 8, v145
	v_lshl_or_b32 v138, s40, 8, v149
	v_ashrrev_i32_e32 v141, 31, v140
	v_readlane_b32 s16, v254, 23
	s_waitcnt lgkmcnt(0)
	v_pk_mul_f32 v[120:121], v[120:121], v[154:155] op_sel_hi:[1,0]
	v_pk_mul_f32 v[124:125], v[124:125], v[154:155] op_sel_hi:[1,0]
	v_pk_mul_f32 v[122:123], v[122:123], v[154:155] op_sel_hi:[1,0]
	v_max_f32_e32 v120, 0, v120
	v_ashrrev_i32_e32 v139, 31, v138
	v_lshlrev_b64 v[142:143], 14, v[140:141]
	v_readlane_b32 s17, v254, 24
	v_pk_mul_f32 v[126:127], v[126:127], v[154:155] op_sel_hi:[1,0]
	v_mul_f32_e32 v141, v120, v120
	v_max_f32_e32 v120, 0, v125
	v_max_f32_e32 v121, 0, v121
	v_max_f32_e32 v122, 0, v122
	v_lshl_add_u64 v[156:157], s[16:17], 0, v[142:143]
	v_lshlrev_b64 v[142:143], 1, v[138:139]
	v_max_f32_e32 v124, 0, v124
	v_mul_f32_e32 v120, v120, v120
	v_mul_f32_e32 v125, v121, v121
	v_max_f32_e32 v121, 0, v126
	v_mul_f32_e32 v126, v122, v122
	v_max_f32_e32 v122, 0, v127
	v_max_f32_e32 v123, 0, v123
	v_pk_mul_f32 v[114:115], v[114:115], v[154:155] op_sel_hi:[1,0]
	v_pk_mul_f32 v[112:113], v[112:113], v[154:155] op_sel_hi:[1,0]
	v_lshl_add_u64 v[138:139], v[156:157], 0, v[142:143]
	v_mul_f32_e32 v124, v124, v124
	v_mul_f32_e32 v121, v121, v121
	v_mul_f32_e32 v122, v122, v122
	v_mul_f32_e32 v123, v123, v123
	v_cvt_pk_bf16_f32 v120, v124, v120
	v_pk_mul_f32 v[118:119], v[118:119], v[154:155] op_sel_hi:[1,0]
	v_pk_mul_f32 v[116:117], v[116:117], v[154:155] op_sel_hi:[1,0]
	v_max_f32_e32 v112, 0, v112
	v_max_f32_e32 v113, 0, v113
	v_max_f32_e32 v114, 0, v114
	v_cvt_pk_bf16_f32 v121, v121, v122
	v_cvt_pk_bf16_f32 v122, v141, v125
	v_cvt_pk_bf16_f32 v123, v126, v123
	flat_store_dwordx4 v[138:139], v[120:123] sc1
	v_max_f32_e32 v115, 0, v115
	v_max_f32_e32 v116, 0, v116
	v_mul_f32_e32 v120, v112, v112
	v_max_f32_e32 v112, 0, v117
	v_mul_f32_e32 v117, v113, v113
	v_max_f32_e32 v113, 0, v118
	v_mul_f32_e32 v118, v114, v114
	v_max_f32_e32 v114, 0, v119
	v_mul_f32_e32 v112, v112, v112
	v_mul_f32_e32 v113, v113, v113
	v_mul_f32_e32 v114, v114, v114
	v_mul_f32_e32 v115, v115, v115
	v_mul_f32_e32 v116, v116, v116
	v_cvt_pk_bf16_f32 v112, v116, v112
	v_cvt_pk_bf16_f32 v113, v113, v114
	v_cvt_pk_bf16_f32 v114, v120, v117
	v_cvt_pk_bf16_f32 v115, v118, v115
	flat_store_dwordx4 v[138:139], v[112:115] offset:256 sc1
	ds_read_b32 v114, v152 offset:64
	s_waitcnt lgkmcnt(0)
	v_pk_mul_f32 v[104:105], v[104:105], v[114:115] op_sel_hi:[1,0]
	v_or_b32_e32 v112, 16, v140
	v_ashrrev_i32_e32 v113, 31, v112
	v_pk_mul_f32 v[108:109], v[108:109], v[114:115] op_sel_hi:[1,0]
	v_pk_mul_f32 v[106:107], v[106:107], v[114:115] op_sel_hi:[1,0]
	v_max_f32_e32 v104, 0, v104
	v_lshlrev_b64 v[112:113], 14, v[112:113]
	v_pk_mul_f32 v[110:111], v[110:111], v[114:115] op_sel_hi:[1,0]
	v_mul_f32_e32 v115, v104, v104
	v_max_f32_e32 v104, 0, v109
	v_max_f32_e32 v105, 0, v105
	v_max_f32_e32 v106, 0, v106
	v_lshl_add_u64 v[112:113], s[16:17], 0, v[112:113]
	v_max_f32_e32 v108, 0, v108
	v_mul_f32_e32 v104, v104, v104
	v_mul_f32_e32 v109, v105, v105
	v_max_f32_e32 v105, 0, v110
	v_mul_f32_e32 v110, v106, v106
	v_max_f32_e32 v106, 0, v111
	v_max_f32_e32 v107, 0, v107
	v_pk_mul_f32 v[98:99], v[98:99], v[114:115] op_sel_hi:[1,0]
	v_pk_mul_f32 v[96:97], v[96:97], v[114:115] op_sel_hi:[1,0]
	v_lshl_add_u64 v[112:113], v[112:113], 0, v[142:143]
	v_mul_f32_e32 v108, v108, v108
	v_mul_f32_e32 v105, v105, v105
	v_mul_f32_e32 v106, v106, v106
	v_mul_f32_e32 v107, v107, v107
	v_cvt_pk_bf16_f32 v104, v108, v104
	v_pk_mul_f32 v[102:103], v[102:103], v[114:115] op_sel_hi:[1,0]
	v_pk_mul_f32 v[100:101], v[100:101], v[114:115] op_sel_hi:[1,0]
	v_max_f32_e32 v96, 0, v96
	v_max_f32_e32 v97, 0, v97
	v_max_f32_e32 v98, 0, v98
	v_cvt_pk_bf16_f32 v105, v105, v106
	v_cvt_pk_bf16_f32 v106, v115, v109
	v_cvt_pk_bf16_f32 v107, v110, v107
	flat_store_dwordx4 v[112:113], v[104:107] sc1
	v_max_f32_e32 v99, 0, v99
	v_max_f32_e32 v100, 0, v100
	v_mul_f32_e32 v104, v96, v96
	v_max_f32_e32 v96, 0, v101
	v_mul_f32_e32 v101, v97, v97
	v_max_f32_e32 v97, 0, v102
	v_mul_f32_e32 v102, v98, v98
	v_max_f32_e32 v98, 0, v103
	v_mul_f32_e32 v96, v96, v96
	v_mul_f32_e32 v97, v97, v97
	v_mul_f32_e32 v98, v98, v98
	v_mul_f32_e32 v99, v99, v99
	v_mul_f32_e32 v100, v100, v100
	v_cvt_pk_bf16_f32 v96, v100, v96
	v_cvt_pk_bf16_f32 v97, v97, v98
	v_cvt_pk_bf16_f32 v98, v104, v101
	v_cvt_pk_bf16_f32 v99, v102, v99
	flat_store_dwordx4 v[112:113], v[96:99] offset:256 sc1
	ds_read_b32 v98, v152 offset:128
	s_waitcnt lgkmcnt(0)
	v_pk_mul_f32 v[88:89], v[88:89], v[98:99] op_sel_hi:[1,0]
	v_or_b32_e32 v96, 32, v140
	v_ashrrev_i32_e32 v97, 31, v96
	v_pk_mul_f32 v[92:93], v[92:93], v[98:99] op_sel_hi:[1,0]
	v_pk_mul_f32 v[90:91], v[90:91], v[98:99] op_sel_hi:[1,0]
	v_max_f32_e32 v88, 0, v88
	v_lshlrev_b64 v[96:97], 14, v[96:97]
	v_pk_mul_f32 v[94:95], v[94:95], v[98:99] op_sel_hi:[1,0]
	v_mul_f32_e32 v99, v88, v88
	v_max_f32_e32 v88, 0, v93
	v_max_f32_e32 v89, 0, v89
	v_max_f32_e32 v90, 0, v90
	v_lshl_add_u64 v[96:97], s[16:17], 0, v[96:97]
	v_max_f32_e32 v92, 0, v92
	v_mul_f32_e32 v88, v88, v88
	v_mul_f32_e32 v93, v89, v89
	v_max_f32_e32 v89, 0, v94
	v_mul_f32_e32 v94, v90, v90
	v_max_f32_e32 v90, 0, v95
	v_max_f32_e32 v91, 0, v91
	v_pk_mul_f32 v[82:83], v[82:83], v[98:99] op_sel_hi:[1,0]
	v_pk_mul_f32 v[80:81], v[80:81], v[98:99] op_sel_hi:[1,0]
	v_lshl_add_u64 v[96:97], v[96:97], 0, v[142:143]
	v_mul_f32_e32 v92, v92, v92
	v_mul_f32_e32 v89, v89, v89
	v_mul_f32_e32 v90, v90, v90
	v_mul_f32_e32 v91, v91, v91
	v_cvt_pk_bf16_f32 v88, v92, v88
	v_pk_mul_f32 v[86:87], v[86:87], v[98:99] op_sel_hi:[1,0]
	v_pk_mul_f32 v[84:85], v[84:85], v[98:99] op_sel_hi:[1,0]
	v_max_f32_e32 v80, 0, v80
	v_max_f32_e32 v81, 0, v81
	v_max_f32_e32 v82, 0, v82
	v_cvt_pk_bf16_f32 v89, v89, v90
	v_cvt_pk_bf16_f32 v90, v99, v93
	v_cvt_pk_bf16_f32 v91, v94, v91
	flat_store_dwordx4 v[96:97], v[88:91] sc1
	v_max_f32_e32 v83, 0, v83
	v_max_f32_e32 v84, 0, v84
	v_mul_f32_e32 v88, v80, v80
	v_max_f32_e32 v80, 0, v85
	v_mul_f32_e32 v85, v81, v81
	v_max_f32_e32 v81, 0, v86
	v_mul_f32_e32 v86, v82, v82
	v_max_f32_e32 v82, 0, v87
	v_mul_f32_e32 v80, v80, v80
	v_mul_f32_e32 v81, v81, v81
	v_mul_f32_e32 v82, v82, v82
	v_mul_f32_e32 v83, v83, v83
	v_mul_f32_e32 v84, v84, v84
	v_cvt_pk_bf16_f32 v80, v84, v80
	v_cvt_pk_bf16_f32 v81, v81, v82
	v_cvt_pk_bf16_f32 v82, v88, v85
	v_cvt_pk_bf16_f32 v83, v86, v83
	flat_store_dwordx4 v[96:97], v[80:83] offset:256 sc1
	ds_read_b32 v82, v152 offset:192
	s_waitcnt lgkmcnt(0)
; #define LAS __attribute__((address_space(3)))
; __device__ __forceinline__ unsigned cvt_pk_bf16(float lo, float hi) { unsigned r; asm volatile("v_cvt_pk_bf16_f32 %0, %1, %2" : "=v"(r) : "v"(lo), "v"(hi)); return r; }
;     __device__ __forceinline__ void stash(unsigned long long v, LAS unsigned char* lds, int par, int tid) const { if (tid < 256) *(LAS float*)(lds + 131072 + par * 1024 + tid * 4) = rsqrtf((float)v * (1.f / (1048576.f * DM)) + EPS_); }
;     __device__ __forceinline__ void operator()(const f32x4 (&acc)[2][2][4][2], const Unit& u, int wr, int wc, int fr, int fq, LAS unsigned char* lds, int par, int npm, int tid) const {
;         const int row0 = u.pm * BM + wr * 64 + fr, col0 = u.pn * BM + wc * 32 + 8 * fq;
;         unsigned long long nx = 0ull; if (npm >= 0) nx = prefetch(npm, tid);
; #pragma unroll
;         for (int ai = 0; ai < 2; ++ai)
; #pragma unroll
;             for (int m = 0; m < 4; ++m) { const int row = row0 + ai * HALF + m * 16; bf16_t* rowp = O + (size_t)row * ldc + col0;
;                 const float rstd = *(const LAS float*)(lds + 131072 + par * 1024 + (wr * 64 + fr + ai * HALF + m * 16) * 4);
; #pragma unroll
;                 for (int bj = 0; bj < 2; ++bj) { f32x4 v0 = acc[ai][bj][m][0] * rstd, v1 = acc[ai][bj][m][1] * rstd;
;                     if (ACT == 1) {
; #pragma unroll
;                         for (int j = 0; j < 4; ++j) { const float a = fmaxf(v0[j], 0.f), b = fmaxf(v1[j], 0.f); v0[j] = a * a; v1[j] = b * b; } }
;                     u32x4 w; w.x = cvt_pk_bf16(v0[0], v0[1]); w.y = cvt_pk_bf16(v0[2], v0[3]); w.z = cvt_pk_bf16(v1[0], v1[1]); w.w = cvt_pk_bf16(v1[2], v1[3]);
;                     *(u32x4*)(rowp + bj * HALF) = w; } }
;         if (npm >= 0) stash(nx, lds, par ^ 1, tid);
	v_pk_mul_f32 v[72:73], v[72:73], v[82:83] op_sel_hi:[1,0]
	v_or_b32_e32 v80, 48, v140
	v_ashrrev_i32_e32 v81, 31, v80
	v_pk_mul_f32 v[76:77], v[76:77], v[82:83] op_sel_hi:[1,0]
	v_pk_mul_f32 v[74:75], v[74:75], v[82:83] op_sel_hi:[1,0]
	v_max_f32_e32 v72, 0, v72
	v_lshlrev_b64 v[80:81], 14, v[80:81]
	v_pk_mul_f32 v[78:79], v[78:79], v[82:83] op_sel_hi:[1,0]
	v_mul_f32_e32 v83, v72, v72
	v_max_f32_e32 v72, 0, v77
	v_max_f32_e32 v73, 0, v73
	v_max_f32_e32 v74, 0, v74
	v_lshl_add_u64 v[80:81], s[16:17], 0, v[80:81]
	v_max_f32_e32 v76, 0, v76
	v_mul_f32_e32 v72, v72, v72
	v_mul_f32_e32 v77, v73, v73
	v_max_f32_e32 v73, 0, v78
	v_mul_f32_e32 v78, v74, v74
	v_max_f32_e32 v74, 0, v79
	v_max_f32_e32 v75, 0, v75
	v_pk_mul_f32 v[66:67], v[66:67], v[82:83] op_sel_hi:[1,0]
	v_pk_mul_f32 v[64:65], v[64:65], v[82:83] op_sel_hi:[1,0]
	v_lshl_add_u64 v[80:81], v[80:81], 0, v[142:143]
	v_mul_f32_e32 v76, v76, v76
	v_mul_f32_e32 v73, v73, v73
	v_mul_f32_e32 v74, v74, v74
	v_mul_f32_e32 v75, v75, v75
	v_cvt_pk_bf16_f32 v72, v76, v72
	v_pk_mul_f32 v[70:71], v[70:71], v[82:83] op_sel_hi:[1,0]
	v_pk_mul_f32 v[68:69], v[68:69], v[82:83] op_sel_hi:[1,0]
	v_max_f32_e32 v64, 0, v64
	v_max_f32_e32 v65, 0, v65
	v_max_f32_e32 v66, 0, v66
	v_cvt_pk_bf16_f32 v73, v73, v74
	v_cvt_pk_bf16_f32 v74, v83, v77
	v_cvt_pk_bf16_f32 v75, v78, v75
	flat_store_dwordx4 v[80:81], v[72:75] sc1
	v_max_f32_e32 v67, 0, v67
	v_max_f32_e32 v68, 0, v68
	v_mul_f32_e32 v72, v64, v64
	v_max_f32_e32 v64, 0, v69
	v_mul_f32_e32 v69, v65, v65
	v_max_f32_e32 v65, 0, v70
	v_mul_f32_e32 v70, v66, v66
	v_max_f32_e32 v66, 0, v71
	v_mul_f32_e32 v64, v64, v64
	v_mul_f32_e32 v65, v65, v65
	v_mul_f32_e32 v66, v66, v66
	v_mul_f32_e32 v67, v67, v67
	v_mul_f32_e32 v68, v68, v68
	v_cvt_pk_bf16_f32 v64, v68, v64
	v_cvt_pk_bf16_f32 v65, v65, v66
	v_cvt_pk_bf16_f32 v66, v72, v69
	v_cvt_pk_bf16_f32 v67, v70, v67
	flat_store_dwordx4 v[80:81], v[64:67] offset:256 sc1
	ds_read_b32 v64, v152 offset:512
	s_mov_b64 s[16:17], 0x200000
	v_lshl_add_u64 v[66:67], v[138:139], 0, s[16:17]
	s_mov_b32 s16, 0x200000
	s_waitcnt lgkmcnt(0)
	v_pk_mul_f32 v[56:57], v[56:57], v[64:65] op_sel_hi:[1,0]
	v_pk_mul_f32 v[60:61], v[60:61], v[64:65] op_sel_hi:[1,0]
	v_pk_mul_f32 v[58:59], v[58:59], v[64:65] op_sel_hi:[1,0]
	v_max_f32_e32 v56, 0, v56
	v_pk_mul_f32 v[62:63], v[62:63], v[64:65] op_sel_hi:[1,0]
	v_max_f32_e32 v60, 0, v60
	v_mul_f32_e32 v65, v56, v56
	v_max_f32_e32 v56, 0, v61
	v_max_f32_e32 v57, 0, v57
	v_max_f32_e32 v58, 0, v58
	v_mul_f32_e32 v60, v60, v60
	v_mul_f32_e32 v56, v56, v56
	v_mul_f32_e32 v61, v57, v57
	v_max_f32_e32 v57, 0, v62
	v_mul_f32_e32 v62, v58, v58
	v_max_f32_e32 v58, 0, v63
	v_mul_f32_e32 v57, v57, v57
	v_max_f32_e32 v59, 0, v59
	v_mul_f32_e32 v58, v58, v58
	v_cvt_pk_bf16_f32 v56, v60, v56
	v_add_co_u32_e32 v60, vcc, s16, v138
	v_pk_mul_f32 v[50:51], v[50:51], v[64:65] op_sel_hi:[1,0]
	v_pk_mul_f32 v[48:49], v[48:49], v[64:65] op_sel_hi:[1,0]
	v_mul_f32_e32 v59, v59, v59
	v_cvt_pk_bf16_f32 v57, v57, v58
	v_cvt_pk_bf16_f32 v58, v65, v61
	v_addc_co_u32_e32 v61, vcc, 0, v139, vcc
	v_pk_mul_f32 v[54:55], v[54:55], v[64:65] op_sel_hi:[1,0]
	v_pk_mul_f32 v[52:53], v[52:53], v[64:65] op_sel_hi:[1,0]
	v_max_f32_e32 v48, 0, v48
	v_max_f32_e32 v49, 0, v49
	v_max_f32_e32 v50, 0, v50
	v_cvt_pk_bf16_f32 v59, v62, v59
	flat_store_dwordx4 v[60:61], v[56:59] sc1
	v_max_f32_e32 v51, 0, v51
	v_max_f32_e32 v52, 0, v52
	v_mul_f32_e32 v56, v48, v48
	v_max_f32_e32 v48, 0, v53
	v_mul_f32_e32 v53, v49, v49
	v_max_f32_e32 v49, 0, v54
	v_mul_f32_e32 v54, v50, v50
	v_max_f32_e32 v50, 0, v55
	v_mul_f32_e32 v48, v48, v48
	v_mul_f32_e32 v49, v49, v49
	v_mul_f32_e32 v50, v50, v50
	v_mul_f32_e32 v51, v51, v51
	v_mul_f32_e32 v52, v52, v52
	v_cvt_pk_bf16_f32 v48, v52, v48
	v_cvt_pk_bf16_f32 v49, v49, v50
	v_cvt_pk_bf16_f32 v50, v56, v53
	v_cvt_pk_bf16_f32 v51, v54, v51
	flat_store_dwordx4 v[66:67], v[48:51] offset:256 sc1
	ds_read_b32 v48, v152 offset:576
	s_mov_b64 s[16:17], 0x240000
	v_lshl_add_u64 v[50:51], v[138:139], 0, s[16:17]
	s_mov_b32 s16, 0x240000
	s_waitcnt lgkmcnt(0)
	v_pk_mul_f32 v[40:41], v[40:41], v[48:49] op_sel_hi:[1,0]
	v_pk_mul_f32 v[44:45], v[44:45], v[48:49] op_sel_hi:[1,0]
	v_pk_mul_f32 v[42:43], v[42:43], v[48:49] op_sel_hi:[1,0]
	v_max_f32_e32 v40, 0, v40
	v_pk_mul_f32 v[46:47], v[46:47], v[48:49] op_sel_hi:[1,0]
	v_max_f32_e32 v44, 0, v44
	v_mul_f32_e32 v49, v40, v40
	v_max_f32_e32 v40, 0, v45
	v_max_f32_e32 v41, 0, v41
	v_max_f32_e32 v42, 0, v42
	v_mul_f32_e32 v44, v44, v44
	v_mul_f32_e32 v40, v40, v40
	v_mul_f32_e32 v45, v41, v41
	v_max_f32_e32 v41, 0, v46
	v_mul_f32_e32 v46, v42, v42
	v_max_f32_e32 v42, 0, v47
	v_mul_f32_e32 v41, v41, v41
	v_max_f32_e32 v43, 0, v43
	v_mul_f32_e32 v42, v42, v42
	v_cvt_pk_bf16_f32 v40, v44, v40
	v_add_co_u32_e32 v44, vcc, s16, v138
	v_pk_mul_f32 v[34:35], v[34:35], v[48:49] op_sel_hi:[1,0]
	v_pk_mul_f32 v[32:33], v[32:33], v[48:49] op_sel_hi:[1,0]
	v_mul_f32_e32 v43, v43, v43
	v_cvt_pk_bf16_f32 v41, v41, v42
	v_cvt_pk_bf16_f32 v42, v49, v45
	v_addc_co_u32_e32 v45, vcc, 0, v139, vcc
	v_pk_mul_f32 v[38:39], v[38:39], v[48:49] op_sel_hi:[1,0]
	v_pk_mul_f32 v[36:37], v[36:37], v[48:49] op_sel_hi:[1,0]
	v_max_f32_e32 v32, 0, v32
	v_max_f32_e32 v33, 0, v33
	v_max_f32_e32 v34, 0, v34
	v_cvt_pk_bf16_f32 v43, v46, v43
	flat_store_dwordx4 v[44:45], v[40:43] sc1
	v_max_f32_e32 v35, 0, v35
	v_max_f32_e32 v36, 0, v36
	v_mul_f32_e32 v40, v32, v32
	v_max_f32_e32 v32, 0, v37
	v_mul_f32_e32 v37, v33, v33
	v_max_f32_e32 v33, 0, v38
	v_mul_f32_e32 v38, v34, v34
	v_max_f32_e32 v34, 0, v39
	v_mul_f32_e32 v32, v32, v32
	v_mul_f32_e32 v33, v33, v33
	v_mul_f32_e32 v34, v34, v34
	v_mul_f32_e32 v35, v35, v35
	v_mul_f32_e32 v36, v36, v36
	v_cvt_pk_bf16_f32 v32, v36, v32
	v_cvt_pk_bf16_f32 v33, v33, v34
	v_cvt_pk_bf16_f32 v34, v40, v37
	v_cvt_pk_bf16_f32 v35, v38, v35
	flat_store_dwordx4 v[50:51], v[32:35] offset:256 sc1
	ds_read_b32 v32, v152 offset:640
	s_mov_b64 s[16:17], 0x280000
	v_lshl_add_u64 v[34:35], v[138:139], 0, s[16:17]
	s_mov_b32 s16, 0x280000
	s_waitcnt lgkmcnt(0)
; #define LAS __attribute__((address_space(3)))
; __device__ __forceinline__ unsigned cvt_pk_bf16(float lo, float hi) { unsigned r; asm volatile("v_cvt_pk_bf16_f32 %0, %1, %2" : "=v"(r) : "v"(lo), "v"(hi)); return r; }
;     __device__ __forceinline__ void stash(unsigned long long v, LAS unsigned char* lds, int par, int tid) const { if (tid < 256) *(LAS float*)(lds + 131072 + par * 1024 + tid * 4) = rsqrtf((float)v * (1.f / (1048576.f * DM)) + EPS_); }
;     __device__ __forceinline__ void operator()(const f32x4 (&acc)[2][2][4][2], const Unit& u, int wr, int wc, int fr, int fq, LAS unsigned char* lds, int par, int npm, int tid) const {
;     ...
;             for (int m = 0; m < 4; ++m) { const int row = row0 + ai * HALF + m * 16; bf16_t* rowp = O + (size_t)row * ldc + col0;
;                 const float rstd = *(const LAS float*)(lds + 131072 + par * 1024 + (wr * 64 + fr + ai * HALF + m * 16) * 4);
; #pragma unroll
;                 for (int bj = 0; bj < 2; ++bj) { f32x4 v0 = acc[ai][bj][m][0] * rstd, v1 = acc[ai][bj][m][1] * rstd;
;                     if (ACT == 1) {
; #pragma unroll
;                         for (int j = 0; j < 4; ++j) { const float a = fmaxf(v0[j], 0.f), b = fmaxf(v1[j], 0.f); v0[j] = a * a; v1[j] = b * b; } }
;                     u32x4 w; w.x = cvt_pk_bf16(v0[0], v0[1]); w.y = cvt_pk_bf16(v0[2], v0[3]); w.z = cvt_pk_bf16(v1[0], v1[1]); w.w = cvt_pk_bf16(v1[2], v1[3]);
;                     *(u32x4*)(rowp + bj * HALF) = w; } }
;         if (npm >= 0) stash(nx, lds, par ^ 1, tid);
	v_pk_mul_f32 v[24:25], v[24:25], v[32:33] op_sel_hi:[1,0]
	v_pk_mul_f32 v[28:29], v[28:29], v[32:33] op_sel_hi:[1,0]
	v_pk_mul_f32 v[26:27], v[26:27], v[32:33] op_sel_hi:[1,0]
	v_max_f32_e32 v24, 0, v24
	v_pk_mul_f32 v[30:31], v[30:31], v[32:33] op_sel_hi:[1,0]
	v_max_f32_e32 v28, 0, v28
	v_mul_f32_e32 v33, v24, v24
	v_max_f32_e32 v24, 0, v29
	v_max_f32_e32 v25, 0, v25
	v_max_f32_e32 v26, 0, v26
	v_mul_f32_e32 v28, v28, v28
	v_mul_f32_e32 v24, v24, v24
	v_mul_f32_e32 v29, v25, v25
	v_max_f32_e32 v25, 0, v30
	v_mul_f32_e32 v30, v26, v26
	v_max_f32_e32 v26, 0, v31
	v_mul_f32_e32 v25, v25, v25
	v_max_f32_e32 v27, 0, v27
	v_mul_f32_e32 v26, v26, v26
	v_cvt_pk_bf16_f32 v24, v28, v24
	v_add_co_u32_e32 v28, vcc, s16, v138
	v_pk_mul_f32 v[18:19], v[18:19], v[32:33] op_sel_hi:[1,0]
	v_pk_mul_f32 v[16:17], v[16:17], v[32:33] op_sel_hi:[1,0]
	v_mul_f32_e32 v27, v27, v27
	v_cvt_pk_bf16_f32 v25, v25, v26
	v_cvt_pk_bf16_f32 v26, v33, v29
	v_addc_co_u32_e32 v29, vcc, 0, v139, vcc
	v_pk_mul_f32 v[22:23], v[22:23], v[32:33] op_sel_hi:[1,0]
	v_pk_mul_f32 v[20:21], v[20:21], v[32:33] op_sel_hi:[1,0]
	v_max_f32_e32 v16, 0, v16
	v_max_f32_e32 v17, 0, v17
	v_max_f32_e32 v18, 0, v18
	v_cvt_pk_bf16_f32 v27, v30, v27
	flat_store_dwordx4 v[28:29], v[24:27] sc1
	v_max_f32_e32 v19, 0, v19
	v_max_f32_e32 v20, 0, v20
	v_mul_f32_e32 v24, v16, v16
	v_max_f32_e32 v16, 0, v21
	v_mul_f32_e32 v21, v17, v17
	v_max_f32_e32 v17, 0, v22
	v_mul_f32_e32 v22, v18, v18
	v_max_f32_e32 v18, 0, v23
	v_mul_f32_e32 v16, v16, v16
	v_mul_f32_e32 v17, v17, v17
	v_mul_f32_e32 v18, v18, v18
	v_mul_f32_e32 v19, v19, v19
	v_mul_f32_e32 v20, v20, v20
	v_cvt_pk_bf16_f32 v16, v20, v16
	v_cvt_pk_bf16_f32 v17, v17, v18
	v_cvt_pk_bf16_f32 v18, v24, v21
	v_cvt_pk_bf16_f32 v19, v22, v19
	flat_store_dwordx4 v[34:35], v[16:19] offset:256 sc1
	ds_read_b32 v16, v152 offset:704
	s_mov_b64 s[16:17], 0x2c0000
	v_lshl_add_u64 v[18:19], v[138:139], 0, s[16:17]
	s_mov_b32 s16, 0x2c0000
	s_waitcnt lgkmcnt(0)
	v_pk_mul_f32 v[8:9], v[8:9], v[16:17] op_sel_hi:[1,0]
	v_pk_mul_f32 v[12:13], v[12:13], v[16:17] op_sel_hi:[1,0]
	v_pk_mul_f32 v[10:11], v[10:11], v[16:17] op_sel_hi:[1,0]
	v_max_f32_e32 v8, 0, v8
	v_pk_mul_f32 v[14:15], v[14:15], v[16:17] op_sel_hi:[1,0]
	v_max_f32_e32 v12, 0, v12
	v_mul_f32_e32 v17, v8, v8
	v_max_f32_e32 v8, 0, v13
	v_max_f32_e32 v9, 0, v9
	v_max_f32_e32 v10, 0, v10
	v_mul_f32_e32 v12, v12, v12
	v_mul_f32_e32 v8, v8, v8
	v_mul_f32_e32 v13, v9, v9
	v_max_f32_e32 v9, 0, v14
	v_mul_f32_e32 v14, v10, v10
	v_max_f32_e32 v10, 0, v15
	v_mul_f32_e32 v9, v9, v9
	v_max_f32_e32 v11, 0, v11
	v_mul_f32_e32 v10, v10, v10
	v_cvt_pk_bf16_f32 v8, v12, v8
	v_add_co_u32_e32 v12, vcc, s16, v138
	v_pk_mul_f32 v[2:3], v[2:3], v[16:17] op_sel_hi:[1,0]
	v_pk_mul_f32 v[0:1], v[0:1], v[16:17] op_sel_hi:[1,0]
	v_mul_f32_e32 v11, v11, v11
	v_cvt_pk_bf16_f32 v9, v9, v10
	v_cvt_pk_bf16_f32 v10, v17, v13
	v_addc_co_u32_e32 v13, vcc, 0, v139, vcc
	v_pk_mul_f32 v[6:7], v[6:7], v[16:17] op_sel_hi:[1,0]
	v_pk_mul_f32 v[4:5], v[4:5], v[16:17] op_sel_hi:[1,0]
	v_max_f32_e32 v0, 0, v0
	v_max_f32_e32 v1, 0, v1
	v_max_f32_e32 v2, 0, v2
	v_cvt_pk_bf16_f32 v11, v14, v11
	flat_store_dwordx4 v[12:13], v[8:11] sc1
	v_max_f32_e32 v3, 0, v3
	v_max_f32_e32 v4, 0, v4
	v_mul_f32_e32 v8, v0, v0
	v_max_f32_e32 v0, 0, v5
	v_mul_f32_e32 v5, v1, v1
	v_max_f32_e32 v1, 0, v6
	v_mul_f32_e32 v6, v2, v2
	v_max_f32_e32 v2, 0, v7
	v_mul_f32_e32 v0, v0, v0
	v_mul_f32_e32 v1, v1, v1
	v_mul_f32_e32 v2, v2, v2
	v_mul_f32_e32 v3, v3, v3
	v_mul_f32_e32 v4, v4, v4
	v_cvt_pk_bf16_f32 v0, v4, v0
	v_cvt_pk_bf16_f32 v1, v1, v2
	v_cvt_pk_bf16_f32 v2, v8, v5
	v_cvt_pk_bf16_f32 v3, v6, v3
	flat_store_dwordx4 v[18:19], v[0:3] offset:256 sc1
	s_and_saveexec_b64 s[16:17], s[14:15]
	s_cbranch_execz .LBB0_151
	s_xor_b32 s14, s18, 0x400
	v_add_u32_e32 v0, s14, v148
	s_mov_b32 s14, 0x800000
	v_cmp_gt_f32_e32 vcc, s14, v151
	v_mul_f32_e32 v1, 0x4b800000, v151
	s_nop 0
	v_cndmask_b32_e32 v1, v151, v1, vcc
	v_rsq_f32_e32 v1, v1
	s_nop 0
	v_mul_f32_e32 v2, 0x45800000, v1
	v_cndmask_b32_e32 v1, v1, v2, vcc
	ds_write_b32 v0, v1
	s_branch .LBB0_151

; __device__ __forceinline__ void unpack8(u32x4 w, float* f) { f[0] = bflo(w.x); f[1] = bfhi(w.x); f[2] = bflo(w.y); f[3] = bfhi(w.y); f[4] = bflo(w.z); f[5] = bfhi(w.z); f[6] = bflo(w.w); f[7] = bfhi(w.w); }
; __device__ __forceinline__ u32x4 pack8(const float* f) { u32x4 w; w.x = cvt_pk_bf16(f[0], f[1]); w.y = cvt_pk_bf16(f[2], f[3]); w.z = cvt_pk_bf16(f[4], f[5]); w.w = cvt_pk_bf16(f[6], f[7]); return w; }
;     __device__ __forceinline__ void operator()(const f32x4 (&acc)[2][2][4][2], const Unit& u, int wr, int wc, int fr, int fq, LAS unsigned char* lds, int par, int npm, int tid) const {
;         const int row0 = u.pm * BM + wr * 64 + fr, col0 = u.pn * BM + wc * 32 + 8 * fq;
;         u32x4 old[2][4][2];
; #pragma unroll
;         for (int ai = 0; ai < 2; ++ai)
; #pragma unroll
;             for (int m = 0; m < 4; ++m)
; #pragma unroll
;                 for (int bj = 0; bj < 2; ++bj) old[ai][m][bj] = *(const u32x4*)(Hb + (size_t)(row0 + ai * HALF + m * 16) * ldc + col0 + bj * HALF);
; #pragma unroll
;         for (int ai = 0; ai < 2; ++ai)
; #pragma unroll
;             for (int m = 0; m < 4; ++m) { const int row = row0 + ai * HALF + m * 16; bf16_t* hp = Hb + (size_t)row * ldc + col0;
;                 float part = 0.f;
; #pragma unroll
;                 for (int bj = 0; bj < 2; ++bj) { float o[8]; unpack8(old[ai][m][bj], o);
;                     const f32x4 a0 = acc[ai][bj][m][0], a1 = acc[ai][bj][m][1];
;                     float v[8] = {o[0] + a0[0], o[1] + a0[1], o[2] + a0[2], o[3] + a0[3], o[4] + a1[0], o[5] + a1[1], o[6] + a1[2], o[7] + a1[3]};
; #pragma unroll
;                     for (int k = 0; k < 8; ++k) part += v[k] * v[k];
;                     *(u32x4*)(hp + bj * HALF) = pack8(v); }
;                 part += __shfl_xor(part, 16); part += __shfl_xor(part, 32);
;                 if (fq == 0) atomicAdd(ssq + row, (unsigned long long)(part * 1048576.f)); }
.LBB0_201:
	v_lshl_or_b32 v212, s38, 8, v246
	v_lshl_add_u32 v228, s37, 8, v201
	v_ashrrev_i32_e32 v213, 31, v212
	v_readlane_b32 s14, v254, 8
	v_lshlrev_b64 v[230:231], 1, v[212:213]
	v_readlane_b32 s15, v254, 9
	v_ashrrev_i32_e32 v229, 31, v228
	v_lshlrev_b64 v[232:233], 12, v[228:229]
	v_lshl_add_u64 v[132:133], s[14:15], 0, v[230:231]
	v_lshl_add_u64 v[128:129], v[132:133], 0, v[232:233]
	flat_load_dwordx4 v[188:191], v[128:129]
	flat_load_dwordx4 v[184:187], v[128:129] offset:256
	v_or_b32_e32 v226, 16, v228
	v_ashrrev_i32_e32 v227, 31, v226
	v_lshlrev_b64 v[128:129], 12, v[226:227]
	v_or_b32_e32 v224, 32, v228
	v_lshl_add_u64 v[128:129], v[132:133], 0, v[128:129]
	v_ashrrev_i32_e32 v225, 31, v224
	flat_load_dwordx4 v[180:183], v[128:129]
	flat_load_dwordx4 v[176:179], v[128:129] offset:256
	v_lshlrev_b64 v[128:129], 12, v[224:225]
	v_or_b32_e32 v222, 48, v228
	v_lshl_add_u64 v[128:129], v[132:133], 0, v[128:129]
	v_ashrrev_i32_e32 v223, 31, v222
	flat_load_dwordx4 v[172:175], v[128:129]
	flat_load_dwordx4 v[168:171], v[128:129] offset:256
	v_lshlrev_b64 v[128:129], 12, v[222:223]
	v_add_u32_e32 v220, 0x80, v228
	v_lshl_add_u64 v[128:129], v[132:133], 0, v[128:129]
	v_ashrrev_i32_e32 v221, 31, v220
	flat_load_dwordx4 v[164:167], v[128:129]
	flat_load_dwordx4 v[160:163], v[128:129] offset:256
	v_lshlrev_b64 v[128:129], 12, v[220:221]
	v_add_u32_e32 v218, 0x90, v228
	v_lshl_add_u64 v[128:129], v[132:133], 0, v[128:129]
	v_ashrrev_i32_e32 v219, 31, v218
	flat_load_dwordx4 v[156:159], v[128:129]
	flat_load_dwordx4 v[152:155], v[128:129] offset:256
	v_lshlrev_b64 v[128:129], 12, v[218:219]
	v_add_u32_e32 v216, 0xa0, v228
	v_add_u32_e32 v214, 0xb0, v228
	v_lshl_add_u64 v[128:129], v[132:133], 0, v[128:129]
	v_ashrrev_i32_e32 v217, 31, v216
	v_ashrrev_i32_e32 v215, 31, v214
	flat_load_dwordx4 v[148:151], v[128:129]
	flat_load_dwordx4 v[144:147], v[128:129] offset:256
	v_lshlrev_b64 v[128:129], 12, v[216:217]
	v_lshlrev_b64 v[134:135], 12, v[214:215]
	v_lshl_add_u64 v[128:129], v[132:133], 0, v[128:129]
	v_lshl_add_u64 v[132:133], v[132:133], 0, v[134:135]
	flat_load_dwordx4 v[136:139], v[128:129]
	s_nop 0
	flat_load_dwordx4 v[128:131], v[128:129] offset:256
	s_nop 0
	flat_load_dwordx4 v[140:143], v[132:133]
	s_nop 0
	flat_load_dwordx4 v[132:135], v[132:133] offset:256
	v_lshl_add_u64 v[232:233], s[14:15], 0, v[232:233]
	v_lshl_add_u64 v[230:231], v[232:233], 0, v[230:231]
	s_waitcnt vmcnt(0) lgkmcnt(0)
	v_lshlrev_b32_e32 v193, 16, v188
	v_and_b32_e32 v188, 0xffff0000, v188
	v_lshlrev_b32_e32 v239, 16, v191
	v_and_b32_e32 v191, 0xffff0000, v191
	v_add_f32_e32 v125, v125, v188
	v_lshlrev_b32_e32 v232, 16, v189
	v_add_f32_e32 v124, v124, v193
	v_add_f32_e32 v123, v123, v191
	v_mul_f32_e32 v191, v125, v125
	v_and_b32_e32 v189, 0xffff0000, v189
	v_add_f32_e32 v126, v126, v232
	v_fmac_f32_e32 v191, v124, v124
	v_lshlrev_b32_e32 v233, 16, v190
	v_add_f32_e32 v127, v127, v189
	v_fmac_f32_e32 v191, v126, v126
	v_and_b32_e32 v190, 0xffff0000, v190
	v_add_f32_e32 v188, v120, v233
	v_fmac_f32_e32 v191, v127, v127
	v_add_f32_e32 v189, v121, v190
	v_fmac_f32_e32 v191, v188, v188
	v_add_f32_e32 v190, v122, v239
	v_fmac_f32_e32 v191, v189, v189
	v_fmac_f32_e32 v191, v190, v190
	v_cvt_pk_bf16_f32 v120, v124, v125
	v_fmac_f32_e32 v191, v123, v123
	v_cvt_pk_bf16_f32 v121, v126, v127
	v_cvt_pk_bf16_f32 v122, v188, v189
	v_cvt_pk_bf16_f32 v123, v190, v123
	flat_store_dwordx4 v[230:231], v[120:123] sc1
	v_lshlrev_b32_e32 v124, 16, v186
	v_and_b32_e32 v125, 0xffff0000, v186
	v_lshlrev_b32_e32 v120, 16, v184
	v_and_b32_e32 v121, 0xffff0000, v184
	v_add_f32_e32 v116, v116, v120
	v_lshlrev_b32_e32 v122, 16, v185
	v_add_f32_e32 v117, v117, v121
	v_fmac_f32_e32 v191, v116, v116
	v_and_b32_e32 v123, 0xffff0000, v185
	v_add_f32_e32 v118, v118, v122
	v_fmac_f32_e32 v191, v117, v117
	v_add_f32_e32 v119, v119, v123
	v_fmac_f32_e32 v191, v118, v118
	v_add_f32_e32 v120, v112, v124
	v_fmac_f32_e32 v191, v119, v119
	v_lshlrev_b32_e32 v126, 16, v187
	v_add_f32_e32 v121, v113, v125
	v_fmac_f32_e32 v191, v120, v120
	v_and_b32_e32 v127, 0xffff0000, v187
	v_add_f32_e32 v122, v114, v126
	v_fmac_f32_e32 v191, v121, v121
	v_add_f32_e32 v115, v115, v127
	v_fmac_f32_e32 v191, v122, v122
	v_cvt_pk_bf16_f32 v112, v116, v117
	v_cvt_pk_bf16_f32 v113, v118, v119
	v_fmac_f32_e32 v191, v115, v115
	v_cvt_pk_bf16_f32 v114, v120, v121
	v_cvt_pk_bf16_f32 v115, v122, v115
	flat_store_dwordx4 v[230:231], v[112:115] offset:256 sc1
	s_nop 1
	v_and_b32_e32 v113, 64, v238
	v_xor_b32_e32 v112, 16, v238
	v_add_u32_e32 v113, 64, v113
	v_cmp_lt_i32_e32 vcc, v112, v113
	v_xor_b32_e32 v115, 32, v238
	s_nop 0
	v_cndmask_b32_e32 v112, v238, v112, vcc
	v_lshlrev_b32_e32 v112, 2, v112
	ds_bpermute_b32 v114, v112, v191
	v_cmp_lt_i32_e32 vcc, v115, v113
	s_waitcnt lgkmcnt(0)
	v_add_f32_e32 v114, v191, v114
	v_cndmask_b32_e32 v113, v238, v115, vcc
	v_lshlrev_b32_e32 v113, 2, v113
	ds_bpermute_b32 v115, v113, v114
	s_and_saveexec_b64 s[14:15], s[4:5]
	s_cbranch_execz .LBB0_203
	s_waitcnt lgkmcnt(0)
	v_add_f32_e32 v114, v114, v115
	v_mul_f32_e32 v114, 0x49800000, v114
	v_trunc_f32_e32 v114, v114
	v_mul_f32_e32 v115, 0x2f800000, v114
	v_floor_f32_e32 v115, v115
	v_fmac_f32_e32 v114, 0xcf800000, v115
	v_cvt_u32_f32_e32 v114, v114
	v_cvt_u32_f32_e32 v115, v115
	v_readlane_b32 s16, v254, 39
	v_readlane_b32 s17, v254, 40
	s_nop 1
	v_lshl_add_u64 v[116:117], v[228:229], 3, s[16:17]
	flat_atomic_add_x2 v[116:117], v[114:115]
; __device__ __forceinline__ void unpack8(u32x4 w, float* f) { f[0] = bflo(w.x); f[1] = bfhi(w.x); f[2] = bflo(w.y); f[3] = bfhi(w.y); f[4] = bflo(w.z); f[5] = bfhi(w.z); f[6] = bflo(w.w); f[7] = bfhi(w.w); }
; __device__ __forceinline__ u32x4 pack8(const float* f) { u32x4 w; w.x = cvt_pk_bf16(f[0], f[1]); w.y = cvt_pk_bf16(f[2], f[3]); w.z = cvt_pk_bf16(f[4], f[5]); w.w = cvt_pk_bf16(f[6], f[7]); return w; }
;     __device__ __forceinline__ void operator()(const f32x4 (&acc)[2][2][4][2], const Unit& u, int wr, int wc, int fr, int fq, LAS unsigned char* lds, int par, int npm, int tid) const {
;     ...
;             for (int m = 0; m < 4; ++m) { const int row = row0 + ai * HALF + m * 16; bf16_t* hp = Hb + (size_t)row * ldc + col0;
;                 float part = 0.f;
; #pragma unroll
;                 for (int bj = 0; bj < 2; ++bj) { float o[8]; unpack8(old[ai][m][bj], o);
;                     const f32x4 a0 = acc[ai][bj][m][0], a1 = acc[ai][bj][m][1];
;                     float v[8] = {o[0] + a0[0], o[1] + a0[1], o[2] + a0[2], o[3] + a0[3], o[4] + a1[0], o[5] + a1[1], o[6] + a1[2], o[7] + a1[3]};
; #pragma unroll
;                     for (int k = 0; k < 8; ++k) part += v[k] * v[k];
;                     *(u32x4*)(hp + bj * HALF) = pack8(v); }
;                 part += __shfl_xor(part, 16); part += __shfl_xor(part, 32);
;                 if (fq == 0) atomicAdd(ssq + row, (unsigned long long)(part * 1048576.f)); }
.LBB0_203:
	s_or_b64 exec, exec, s[14:15]
	v_and_b32_e32 v117, 0xffff0000, v180
	v_lshlrev_b32_e32 v116, 16, v180
	v_and_b32_e32 v119, 0xffff0000, v181
	v_add_f32_e32 v109, v109, v117
	v_lshlrev_b32_e32 v118, 16, v181
	v_add_f32_e32 v108, v108, v116
	v_add_f32_e32 v111, v111, v119
	v_mul_f32_e32 v119, v109, v109
	v_add_f32_e32 v110, v110, v118
	v_fmac_f32_e32 v119, v108, v108
	v_lshlrev_b32_e32 v120, 16, v182
	v_fmac_f32_e32 v119, v110, v110
	v_and_b32_e32 v121, 0xffff0000, v182
	v_add_f32_e32 v116, v104, v120
	v_fmac_f32_e32 v119, v111, v111
	v_lshlrev_b32_e32 v122, 16, v183
	v_add_f32_e32 v117, v105, v121
	v_fmac_f32_e32 v119, v116, v116
	v_and_b32_e32 v123, 0xffff0000, v183
	v_add_f32_e32 v118, v106, v122
	v_fmac_f32_e32 v119, v117, v117
	v_add_f32_e32 v107, v107, v123
	v_fmac_f32_e32 v119, v118, v118
	v_lshlrev_b32_e32 v106, 16, v176
	v_fmac_f32_e32 v119, v107, v107
	v_cvt_pk_bf16_f32 v104, v108, v109
	v_and_b32_e32 v108, 0xffff0000, v176
	v_add_f32_e32 v100, v100, v106
	v_lshlrev_b32_e32 v109, 16, v177
	v_add_f32_e32 v101, v101, v108
	v_fmac_f32_e32 v119, v100, v100
	v_cvt_pk_bf16_f32 v105, v110, v111
	v_and_b32_e32 v110, 0xffff0000, v177
	v_add_f32_e32 v102, v102, v109
	v_fmac_f32_e32 v119, v101, v101
	v_lshlrev_b32_e32 v111, 16, v178
	v_add_f32_e32 v103, v103, v110
	v_fmac_f32_e32 v119, v102, v102
	v_and_b32_e32 v120, 0xffff0000, v178
	v_add_f32_e32 v108, v96, v111
	v_fmac_f32_e32 v119, v103, v103
	v_lshlrev_b32_e32 v121, 16, v179
	v_add_f32_e32 v109, v97, v120
	v_fmac_f32_e32 v119, v108, v108
	v_and_b32_e32 v122, 0xffff0000, v179
	v_add_f32_e32 v110, v98, v121
	v_fmac_f32_e32 v119, v109, v109
	v_add_f32_e32 v111, v99, v122
	v_fmac_f32_e32 v119, v110, v110
	v_fmac_f32_e32 v119, v111, v111
	ds_bpermute_b32 v96, v112, v119
	v_readlane_b32 s14, v254, 8
	s_waitcnt lgkmcnt(0)
	v_lshlrev_b64 v[114:115], 11, v[226:227]
	v_readlane_b32 s15, v254, 9
	v_cvt_pk_bf16_f32 v106, v116, v117
	v_add_f32_e32 v96, v119, v96
	ds_bpermute_b32 v97, v113, v96
	v_lshl_add_u64 v[114:115], v[114:115], 1, s[14:15]
	v_lshl_add_u64 v[114:115], v[212:213], 1, v[114:115]
	v_cvt_pk_bf16_f32 v107, v118, v107
	flat_store_dwordx4 v[114:115], v[104:107] sc1
	v_cvt_pk_bf16_f32 v98, v100, v101
	v_cvt_pk_bf16_f32 v99, v102, v103
	v_cvt_pk_bf16_f32 v100, v108, v109
	v_cvt_pk_bf16_f32 v101, v110, v111
	flat_store_dwordx4 v[114:115], v[98:101] offset:256 sc1
	s_and_saveexec_b64 s[14:15], s[4:5]
	s_cbranch_execz .LBB0_205
	s_waitcnt lgkmcnt(0)
	v_add_f32_e32 v96, v96, v97
	v_mul_f32_e32 v96, 0x49800000, v96
	v_trunc_f32_e32 v96, v96
	v_mul_f32_e32 v97, 0x2f800000, v96
	v_floor_f32_e32 v97, v97
	v_fmac_f32_e32 v96, 0xcf800000, v97
	v_cvt_u32_f32_e32 v96, v96
	v_cvt_u32_f32_e32 v97, v97
	v_readlane_b32 s16, v254, 39
	v_readlane_b32 s17, v254, 40
	s_nop 1
	v_lshl_add_u64 v[98:99], v[226:227], 3, s[16:17]
	flat_atomic_add_x2 v[98:99], v[96:97]
.LBB0_205:
	s_or_b64 exec, exec, s[14:15]
	v_and_b32_e32 v99, 0xffff0000, v172
	v_lshlrev_b32_e32 v98, 16, v172
	v_and_b32_e32 v101, 0xffff0000, v173
	v_add_f32_e32 v93, v93, v99
	v_lshlrev_b32_e32 v100, 16, v173
	v_add_f32_e32 v92, v92, v98
	v_add_f32_e32 v95, v95, v101
	v_mul_f32_e32 v101, v93, v93
	v_add_f32_e32 v94, v94, v100
	v_fmac_f32_e32 v101, v92, v92
	v_lshlrev_b32_e32 v102, 16, v174
	v_fmac_f32_e32 v101, v94, v94
	v_and_b32_e32 v103, 0xffff0000, v174
	v_add_f32_e32 v98, v88, v102
	v_fmac_f32_e32 v101, v95, v95
	v_lshlrev_b32_e32 v104, 16, v175
	v_add_f32_e32 v99, v89, v103
	v_fmac_f32_e32 v101, v98, v98
	v_and_b32_e32 v105, 0xffff0000, v175
	v_add_f32_e32 v100, v90, v104
	v_fmac_f32_e32 v101, v99, v99
	v_add_f32_e32 v91, v91, v105
	v_fmac_f32_e32 v101, v100, v100
	v_lshlrev_b32_e32 v90, 16, v168
	v_fmac_f32_e32 v101, v91, v91
	v_cvt_pk_bf16_f32 v88, v92, v93
	v_and_b32_e32 v92, 0xffff0000, v168
	v_add_f32_e32 v84, v84, v90
	v_lshlrev_b32_e32 v93, 16, v169
	v_add_f32_e32 v85, v85, v92
	v_fmac_f32_e32 v101, v84, v84
	v_cvt_pk_bf16_f32 v89, v94, v95
	v_and_b32_e32 v94, 0xffff0000, v169
	v_add_f32_e32 v86, v86, v93
	v_fmac_f32_e32 v101, v85, v85
	v_lshlrev_b32_e32 v95, 16, v170
	v_add_f32_e32 v87, v87, v94
	v_fmac_f32_e32 v101, v86, v86
	v_and_b32_e32 v102, 0xffff0000, v170
	v_add_f32_e32 v92, v80, v95
	v_fmac_f32_e32 v101, v87, v87
	v_lshlrev_b32_e32 v103, 16, v171
	v_add_f32_e32 v93, v81, v102
	v_fmac_f32_e32 v101, v92, v92
	v_and_b32_e32 v104, 0xffff0000, v171
	v_add_f32_e32 v94, v82, v103
	v_fmac_f32_e32 v101, v93, v93
	v_add_f32_e32 v95, v83, v104
	v_fmac_f32_e32 v101, v94, v94
	v_fmac_f32_e32 v101, v95, v95
	ds_bpermute_b32 v80, v112, v101
	v_readlane_b32 s14, v254, 8
	s_waitcnt lgkmcnt(0)
	v_lshlrev_b64 v[96:97], 11, v[224:225]
	v_readlane_b32 s15, v254, 9
	v_cvt_pk_bf16_f32 v90, v98, v99
	v_add_f32_e32 v80, v101, v80
	ds_bpermute_b32 v81, v113, v80
	v_lshl_add_u64 v[96:97], v[96:97], 1, s[14:15]
	v_lshl_add_u64 v[96:97], v[212:213], 1, v[96:97]
	v_cvt_pk_bf16_f32 v91, v100, v91
	flat_store_dwordx4 v[96:97], v[88:91] sc1
	v_cvt_pk_bf16_f32 v82, v84, v85
	v_cvt_pk_bf16_f32 v83, v86, v87
	v_cvt_pk_bf16_f32 v84, v92, v93
	v_cvt_pk_bf16_f32 v85, v94, v95
	flat_store_dwordx4 v[96:97], v[82:85] offset:256 sc1
	s_and_saveexec_b64 s[14:15], s[4:5]
	s_cbranch_execz .LBB0_207
	s_waitcnt lgkmcnt(0)
	v_add_f32_e32 v80, v80, v81
	v_mul_f32_e32 v80, 0x49800000, v80
	v_trunc_f32_e32 v80, v80
	v_mul_f32_e32 v81, 0x2f800000, v80
	v_floor_f32_e32 v81, v81
	v_fmac_f32_e32 v80, 0xcf800000, v81
	v_cvt_u32_f32_e32 v80, v80
	v_cvt_u32_f32_e32 v81, v81
	v_readlane_b32 s16, v254, 39
	v_readlane_b32 s17, v254, 40
	s_nop 1
	v_lshl_add_u64 v[82:83], v[224:225], 3, s[16:17]
	flat_atomic_add_x2 v[82:83], v[80:81]
; __device__ __forceinline__ void unpack8(u32x4 w, float* f) { f[0] = bflo(w.x); f[1] = bfhi(w.x); f[2] = bflo(w.y); f[3] = bfhi(w.y); f[4] = bflo(w.z); f[5] = bfhi(w.z); f[6] = bflo(w.w); f[7] = bfhi(w.w); }
; __device__ __forceinline__ u32x4 pack8(const float* f) { u32x4 w; w.x = cvt_pk_bf16(f[0], f[1]); w.y = cvt_pk_bf16(f[2], f[3]); w.z = cvt_pk_bf16(f[4], f[5]); w.w = cvt_pk_bf16(f[6], f[7]); return w; }
;     __device__ __forceinline__ void operator()(const f32x4 (&acc)[2][2][4][2], const Unit& u, int wr, int wc, int fr, int fq, LAS unsigned char* lds, int par, int npm, int tid) const {
;     ...
;             for (int m = 0; m < 4; ++m) { const int row = row0 + ai * HALF + m * 16; bf16_t* hp = Hb + (size_t)row * ldc + col0;
;                 float part = 0.f;
; #pragma unroll
;                 for (int bj = 0; bj < 2; ++bj) { float o[8]; unpack8(old[ai][m][bj], o);
;                     const f32x4 a0 = acc[ai][bj][m][0], a1 = acc[ai][bj][m][1];
;                     float v[8] = {o[0] + a0[0], o[1] + a0[1], o[2] + a0[2], o[3] + a0[3], o[4] + a1[0], o[5] + a1[1], o[6] + a1[2], o[7] + a1[3]};
; #pragma unroll
;                     for (int k = 0; k < 8; ++k) part += v[k] * v[k];
;                     *(u32x4*)(hp + bj * HALF) = pack8(v); }
;                 part += __shfl_xor(part, 16); part += __shfl_xor(part, 32);
;                 if (fq == 0) atomicAdd(ssq + row, (unsigned long long)(part * 1048576.f)); }
.LBB0_207:
	s_or_b64 exec, exec, s[14:15]
	v_and_b32_e32 v83, 0xffff0000, v164
	v_lshlrev_b32_e32 v82, 16, v164
	v_and_b32_e32 v85, 0xffff0000, v165
	v_add_f32_e32 v77, v77, v83
	v_lshlrev_b32_e32 v84, 16, v165
	v_add_f32_e32 v76, v76, v82
	v_add_f32_e32 v79, v79, v85
	v_mul_f32_e32 v85, v77, v77
	v_add_f32_e32 v78, v78, v84
	v_fmac_f32_e32 v85, v76, v76
	v_lshlrev_b32_e32 v86, 16, v166
	v_fmac_f32_e32 v85, v78, v78
	v_and_b32_e32 v87, 0xffff0000, v166
	v_add_f32_e32 v82, v72, v86
	v_fmac_f32_e32 v85, v79, v79
	v_lshlrev_b32_e32 v88, 16, v167
	v_add_f32_e32 v83, v73, v87
	v_fmac_f32_e32 v85, v82, v82
	v_and_b32_e32 v89, 0xffff0000, v167
	v_add_f32_e32 v84, v74, v88
	v_fmac_f32_e32 v85, v83, v83
	v_add_f32_e32 v75, v75, v89
	v_fmac_f32_e32 v85, v84, v84
	v_lshlrev_b32_e32 v74, 16, v160
	v_fmac_f32_e32 v85, v75, v75
	v_cvt_pk_bf16_f32 v72, v76, v77
	v_and_b32_e32 v76, 0xffff0000, v160
	v_add_f32_e32 v68, v68, v74
	v_lshlrev_b32_e32 v77, 16, v161
	v_add_f32_e32 v69, v69, v76
	v_fmac_f32_e32 v85, v68, v68
	v_cvt_pk_bf16_f32 v73, v78, v79
	v_and_b32_e32 v78, 0xffff0000, v161
	v_add_f32_e32 v70, v70, v77
	v_fmac_f32_e32 v85, v69, v69
	v_lshlrev_b32_e32 v79, 16, v162
	v_add_f32_e32 v71, v71, v78
	v_fmac_f32_e32 v85, v70, v70
	v_and_b32_e32 v86, 0xffff0000, v162
	v_add_f32_e32 v76, v64, v79
	v_fmac_f32_e32 v85, v71, v71
	v_lshlrev_b32_e32 v87, 16, v163
	v_add_f32_e32 v77, v65, v86
	v_fmac_f32_e32 v85, v76, v76
	v_and_b32_e32 v88, 0xffff0000, v163
	v_add_f32_e32 v78, v66, v87
	v_fmac_f32_e32 v85, v77, v77
	v_add_f32_e32 v79, v67, v88
	v_fmac_f32_e32 v85, v78, v78
	v_fmac_f32_e32 v85, v79, v79
	ds_bpermute_b32 v64, v112, v85
	v_readlane_b32 s14, v254, 8
	s_waitcnt lgkmcnt(0)
	v_lshlrev_b64 v[80:81], 11, v[222:223]
	v_readlane_b32 s15, v254, 9
	v_cvt_pk_bf16_f32 v74, v82, v83
	v_add_f32_e32 v64, v85, v64
	ds_bpermute_b32 v65, v113, v64
	v_lshl_add_u64 v[80:81], v[80:81], 1, s[14:15]
	v_lshl_add_u64 v[80:81], v[212:213], 1, v[80:81]
	v_cvt_pk_bf16_f32 v75, v84, v75
	flat_store_dwordx4 v[80:81], v[72:75] sc1
	v_cvt_pk_bf16_f32 v66, v68, v69
	v_cvt_pk_bf16_f32 v67, v70, v71
	v_cvt_pk_bf16_f32 v68, v76, v77
	v_cvt_pk_bf16_f32 v69, v78, v79
	flat_store_dwordx4 v[80:81], v[66:69] offset:256 sc1
	s_and_saveexec_b64 s[14:15], s[4:5]
	s_cbranch_execz .LBB0_209
	s_waitcnt lgkmcnt(0)
	v_add_f32_e32 v64, v64, v65
	v_mul_f32_e32 v64, 0x49800000, v64
	v_trunc_f32_e32 v64, v64
	v_mul_f32_e32 v65, 0x2f800000, v64
	v_floor_f32_e32 v65, v65
	v_fmac_f32_e32 v64, 0xcf800000, v65
	v_cvt_u32_f32_e32 v64, v64
	v_cvt_u32_f32_e32 v65, v65
	v_readlane_b32 s16, v254, 39
	v_readlane_b32 s17, v254, 40
	s_nop 1
	v_lshl_add_u64 v[66:67], v[222:223], 3, s[16:17]
	flat_atomic_add_x2 v[66:67], v[64:65]
.LBB0_209:
	s_or_b64 exec, exec, s[14:15]
	v_and_b32_e32 v67, 0xffff0000, v156
	v_lshlrev_b32_e32 v66, 16, v156
	v_and_b32_e32 v69, 0xffff0000, v157
	v_add_f32_e32 v61, v61, v67
	v_lshlrev_b32_e32 v68, 16, v157
	v_add_f32_e32 v60, v60, v66
	v_add_f32_e32 v63, v63, v69
	v_mul_f32_e32 v69, v61, v61
	v_add_f32_e32 v62, v62, v68
	v_fmac_f32_e32 v69, v60, v60
	v_lshlrev_b32_e32 v70, 16, v158
	v_fmac_f32_e32 v69, v62, v62
	v_and_b32_e32 v71, 0xffff0000, v158
	v_add_f32_e32 v66, v56, v70
	v_fmac_f32_e32 v69, v63, v63
	v_lshlrev_b32_e32 v72, 16, v159
	v_add_f32_e32 v67, v57, v71
	v_fmac_f32_e32 v69, v66, v66
	v_and_b32_e32 v73, 0xffff0000, v159
	v_add_f32_e32 v68, v58, v72
	v_fmac_f32_e32 v69, v67, v67
	v_add_f32_e32 v59, v59, v73
	v_fmac_f32_e32 v69, v68, v68
	v_lshlrev_b32_e32 v58, 16, v152
	v_fmac_f32_e32 v69, v59, v59
	v_cvt_pk_bf16_f32 v56, v60, v61
	v_and_b32_e32 v60, 0xffff0000, v152
	v_add_f32_e32 v52, v52, v58
	v_lshlrev_b32_e32 v61, 16, v153
	v_add_f32_e32 v53, v53, v60
	v_fmac_f32_e32 v69, v52, v52
	v_cvt_pk_bf16_f32 v57, v62, v63
	v_and_b32_e32 v62, 0xffff0000, v153
	v_add_f32_e32 v54, v54, v61
	v_fmac_f32_e32 v69, v53, v53
	v_lshlrev_b32_e32 v63, 16, v154
	v_add_f32_e32 v55, v55, v62
	v_fmac_f32_e32 v69, v54, v54
	v_and_b32_e32 v70, 0xffff0000, v154
	v_add_f32_e32 v60, v48, v63
	v_fmac_f32_e32 v69, v55, v55
	v_lshlrev_b32_e32 v71, 16, v155
	v_add_f32_e32 v61, v49, v70
	v_fmac_f32_e32 v69, v60, v60
	v_and_b32_e32 v72, 0xffff0000, v155
	v_add_f32_e32 v62, v50, v71
	v_fmac_f32_e32 v69, v61, v61
	v_add_f32_e32 v63, v51, v72
	v_fmac_f32_e32 v69, v62, v62
	v_fmac_f32_e32 v69, v63, v63
	ds_bpermute_b32 v48, v112, v69
	v_readlane_b32 s14, v254, 8
	s_waitcnt lgkmcnt(0)
	v_lshlrev_b64 v[64:65], 11, v[220:221]
	v_readlane_b32 s15, v254, 9
	v_cvt_pk_bf16_f32 v58, v66, v67
	v_add_f32_e32 v48, v69, v48
	ds_bpermute_b32 v49, v113, v48
	v_lshl_add_u64 v[64:65], v[64:65], 1, s[14:15]
	v_lshl_add_u64 v[64:65], v[212:213], 1, v[64:65]
	v_cvt_pk_bf16_f32 v59, v68, v59
	flat_store_dwordx4 v[64:65], v[56:59] sc1
	v_cvt_pk_bf16_f32 v50, v52, v53
	v_cvt_pk_bf16_f32 v51, v54, v55
	v_cvt_pk_bf16_f32 v52, v60, v61
	v_cvt_pk_bf16_f32 v53, v62, v63
	flat_store_dwordx4 v[64:65], v[50:53] offset:256 sc1
	s_and_saveexec_b64 s[14:15], s[4:5]
	s_cbranch_execz .LBB0_211
	s_waitcnt lgkmcnt(0)
	v_add_f32_e32 v48, v48, v49
	v_mul_f32_e32 v48, 0x49800000, v48
	v_trunc_f32_e32 v48, v48
	v_mul_f32_e32 v49, 0x2f800000, v48
	v_floor_f32_e32 v49, v49
	v_fmac_f32_e32 v48, 0xcf800000, v49
	v_cvt_u32_f32_e32 v48, v48
	v_cvt_u32_f32_e32 v49, v49
	v_readlane_b32 s16, v254, 39
	v_readlane_b32 s17, v254, 40
	s_nop 1
	v_lshl_add_u64 v[50:51], v[220:221], 3, s[16:17]
	flat_atomic_add_x2 v[50:51], v[48:49]
; __device__ __forceinline__ void unpack8(u32x4 w, float* f) { f[0] = bflo(w.x); f[1] = bfhi(w.x); f[2] = bflo(w.y); f[3] = bfhi(w.y); f[4] = bflo(w.z); f[5] = bfhi(w.z); f[6] = bflo(w.w); f[7] = bfhi(w.w); }
; __device__ __forceinline__ u32x4 pack8(const float* f) { u32x4 w; w.x = cvt_pk_bf16(f[0], f[1]); w.y = cvt_pk_bf16(f[2], f[3]); w.z = cvt_pk_bf16(f[4], f[5]); w.w = cvt_pk_bf16(f[6], f[7]); return w; }
;     __device__ __forceinline__ void operator()(const f32x4 (&acc)[2][2][4][2], const Unit& u, int wr, int wc, int fr, int fq, LAS unsigned char* lds, int par, int npm, int tid) const {
;     ...
;             for (int m = 0; m < 4; ++m) { const int row = row0 + ai * HALF + m * 16; bf16_t* hp = Hb + (size_t)row * ldc + col0;
;                 float part = 0.f;
; #pragma unroll
;                 for (int bj = 0; bj < 2; ++bj) { float o[8]; unpack8(old[ai][m][bj], o);
;                     const f32x4 a0 = acc[ai][bj][m][0], a1 = acc[ai][bj][m][1];
;                     float v[8] = {o[0] + a0[0], o[1] + a0[1], o[2] + a0[2], o[3] + a0[3], o[4] + a1[0], o[5] + a1[1], o[6] + a1[2], o[7] + a1[3]};
; #pragma unroll
;                     for (int k = 0; k < 8; ++k) part += v[k] * v[k];
;                     *(u32x4*)(hp + bj * HALF) = pack8(v); }
;                 part += __shfl_xor(part, 16); part += __shfl_xor(part, 32);
;                 if (fq == 0) atomicAdd(ssq + row, (unsigned long long)(part * 1048576.f)); }
.LBB0_211:
	s_or_b64 exec, exec, s[14:15]
	v_and_b32_e32 v51, 0xffff0000, v148
	v_lshlrev_b32_e32 v50, 16, v148
	v_and_b32_e32 v53, 0xffff0000, v149
	v_add_f32_e32 v45, v45, v51
	v_lshlrev_b32_e32 v52, 16, v149
	v_add_f32_e32 v44, v44, v50
	v_add_f32_e32 v47, v47, v53
	v_mul_f32_e32 v53, v45, v45
	v_add_f32_e32 v46, v46, v52
	v_fmac_f32_e32 v53, v44, v44
	v_lshlrev_b32_e32 v54, 16, v150
	v_fmac_f32_e32 v53, v46, v46
	v_and_b32_e32 v55, 0xffff0000, v150
	v_add_f32_e32 v50, v40, v54
	v_fmac_f32_e32 v53, v47, v47
	v_lshlrev_b32_e32 v56, 16, v151
	v_add_f32_e32 v51, v41, v55
	v_fmac_f32_e32 v53, v50, v50
	v_and_b32_e32 v57, 0xffff0000, v151
	v_add_f32_e32 v52, v42, v56
	v_fmac_f32_e32 v53, v51, v51
	v_add_f32_e32 v43, v43, v57
	v_fmac_f32_e32 v53, v52, v52
	v_lshlrev_b32_e32 v42, 16, v144
	v_fmac_f32_e32 v53, v43, v43
	v_cvt_pk_bf16_f32 v40, v44, v45
	v_and_b32_e32 v44, 0xffff0000, v144
	v_add_f32_e32 v36, v36, v42
	v_lshlrev_b32_e32 v45, 16, v145
	v_add_f32_e32 v37, v37, v44
	v_fmac_f32_e32 v53, v36, v36
	v_cvt_pk_bf16_f32 v41, v46, v47
	v_and_b32_e32 v46, 0xffff0000, v145
	v_add_f32_e32 v38, v38, v45
	v_fmac_f32_e32 v53, v37, v37
	v_lshlrev_b32_e32 v47, 16, v146
	v_add_f32_e32 v39, v39, v46
	v_fmac_f32_e32 v53, v38, v38
	v_and_b32_e32 v54, 0xffff0000, v146
	v_add_f32_e32 v44, v32, v47
	v_fmac_f32_e32 v53, v39, v39
	v_lshlrev_b32_e32 v55, 16, v147
	v_add_f32_e32 v45, v33, v54
	v_fmac_f32_e32 v53, v44, v44
	v_and_b32_e32 v56, 0xffff0000, v147
	v_add_f32_e32 v46, v34, v55
	v_fmac_f32_e32 v53, v45, v45
	v_add_f32_e32 v47, v35, v56
	v_fmac_f32_e32 v53, v46, v46
	v_fmac_f32_e32 v53, v47, v47
	ds_bpermute_b32 v32, v112, v53
	v_readlane_b32 s14, v254, 8
	s_waitcnt lgkmcnt(0)
	v_lshlrev_b64 v[48:49], 11, v[218:219]
	v_readlane_b32 s15, v254, 9
	v_cvt_pk_bf16_f32 v42, v50, v51
	v_add_f32_e32 v32, v53, v32
	ds_bpermute_b32 v33, v113, v32
	v_lshl_add_u64 v[48:49], v[48:49], 1, s[14:15]
	v_lshl_add_u64 v[48:49], v[212:213], 1, v[48:49]
	v_cvt_pk_bf16_f32 v43, v52, v43
	flat_store_dwordx4 v[48:49], v[40:43] sc1
	v_cvt_pk_bf16_f32 v34, v36, v37
	v_cvt_pk_bf16_f32 v35, v38, v39
	v_cvt_pk_bf16_f32 v36, v44, v45
	v_cvt_pk_bf16_f32 v37, v46, v47
	flat_store_dwordx4 v[48:49], v[34:37] offset:256 sc1
	s_and_saveexec_b64 s[14:15], s[4:5]
	s_cbranch_execz .LBB0_213
	s_waitcnt lgkmcnt(0)
	v_add_f32_e32 v32, v32, v33
	v_mul_f32_e32 v32, 0x49800000, v32
	v_trunc_f32_e32 v32, v32
	v_mul_f32_e32 v33, 0x2f800000, v32
	v_floor_f32_e32 v33, v33
	v_fmac_f32_e32 v32, 0xcf800000, v33
	v_cvt_u32_f32_e32 v32, v32
	v_cvt_u32_f32_e32 v33, v33
	v_readlane_b32 s16, v254, 39
	v_readlane_b32 s17, v254, 40
	s_nop 1
	v_lshl_add_u64 v[34:35], v[218:219], 3, s[16:17]
	flat_atomic_add_x2 v[34:35], v[32:33]
; __device__ __forceinline__ void unpack8(u32x4 w, float* f) { f[0] = bflo(w.x); f[1] = bfhi(w.x); f[2] = bflo(w.y); f[3] = bfhi(w.y); f[4] = bflo(w.z); f[5] = bfhi(w.z); f[6] = bflo(w.w); f[7] = bfhi(w.w); }
; __device__ __forceinline__ u32x4 pack8(const float* f) { u32x4 w; w.x = cvt_pk_bf16(f[0], f[1]); w.y = cvt_pk_bf16(f[2], f[3]); w.z = cvt_pk_bf16(f[4], f[5]); w.w = cvt_pk_bf16(f[6], f[7]); return w; }
;     __device__ __forceinline__ void operator()(const f32x4 (&acc)[2][2][4][2], const Unit& u, int wr, int wc, int fr, int fq, LAS unsigned char* lds, int par, int npm, int tid) const {
;     ...
;             for (int m = 0; m < 4; ++m) { const int row = row0 + ai * HALF + m * 16; bf16_t* hp = Hb + (size_t)row * ldc + col0;
;                 float part = 0.f;
; #pragma unroll
;                 for (int bj = 0; bj < 2; ++bj) { float o[8]; unpack8(old[ai][m][bj], o);
;                     const f32x4 a0 = acc[ai][bj][m][0], a1 = acc[ai][bj][m][1];
;                     float v[8] = {o[0] + a0[0], o[1] + a0[1], o[2] + a0[2], o[3] + a0[3], o[4] + a1[0], o[5] + a1[1], o[6] + a1[2], o[7] + a1[3]};
; #pragma unroll
;                     for (int k = 0; k < 8; ++k) part += v[k] * v[k];
;                     *(u32x4*)(hp + bj * HALF) = pack8(v); }
;                 part += __shfl_xor(part, 16); part += __shfl_xor(part, 32);
;                 if (fq == 0) atomicAdd(ssq + row, (unsigned long long)(part * 1048576.f)); }
.LBB0_213:
	s_or_b64 exec, exec, s[14:15]
	v_and_b32_e32 v35, 0xffff0000, v136
	v_lshlrev_b32_e32 v34, 16, v136
	v_and_b32_e32 v37, 0xffff0000, v137
	v_add_f32_e32 v29, v29, v35
	v_lshlrev_b32_e32 v36, 16, v137
	v_add_f32_e32 v28, v28, v34
	v_add_f32_e32 v31, v31, v37
	v_mul_f32_e32 v37, v29, v29
	v_add_f32_e32 v30, v30, v36
	v_fmac_f32_e32 v37, v28, v28
	v_lshlrev_b32_e32 v38, 16, v138
	v_fmac_f32_e32 v37, v30, v30
	v_and_b32_e32 v39, 0xffff0000, v138
	v_add_f32_e32 v34, v24, v38
	v_fmac_f32_e32 v37, v31, v31
	v_lshlrev_b32_e32 v40, 16, v139
	v_add_f32_e32 v35, v25, v39
	v_fmac_f32_e32 v37, v34, v34
	v_and_b32_e32 v41, 0xffff0000, v139
	v_add_f32_e32 v36, v26, v40
	v_fmac_f32_e32 v37, v35, v35
	v_add_f32_e32 v27, v27, v41
	v_fmac_f32_e32 v37, v36, v36
	v_lshlrev_b32_e32 v26, 16, v128
	v_fmac_f32_e32 v37, v27, v27
	v_cvt_pk_bf16_f32 v24, v28, v29
	v_and_b32_e32 v28, 0xffff0000, v128
	v_add_f32_e32 v20, v20, v26
	v_lshlrev_b32_e32 v29, 16, v129
	v_add_f32_e32 v21, v21, v28
	v_fmac_f32_e32 v37, v20, v20
	v_cvt_pk_bf16_f32 v25, v30, v31
	v_and_b32_e32 v30, 0xffff0000, v129
	v_add_f32_e32 v22, v22, v29
	v_fmac_f32_e32 v37, v21, v21
	v_lshlrev_b32_e32 v31, 16, v130
	v_add_f32_e32 v23, v23, v30
	v_fmac_f32_e32 v37, v22, v22
	v_and_b32_e32 v38, 0xffff0000, v130
	v_add_f32_e32 v28, v16, v31
	v_fmac_f32_e32 v37, v23, v23
	v_lshlrev_b32_e32 v39, 16, v131
	v_add_f32_e32 v29, v17, v38
	v_fmac_f32_e32 v37, v28, v28
	v_and_b32_e32 v40, 0xffff0000, v131
	v_add_f32_e32 v30, v18, v39
	v_fmac_f32_e32 v37, v29, v29
	v_add_f32_e32 v31, v19, v40
	v_fmac_f32_e32 v37, v30, v30
	v_fmac_f32_e32 v37, v31, v31
	ds_bpermute_b32 v16, v112, v37
	v_readlane_b32 s14, v254, 8
	s_waitcnt lgkmcnt(0)
	v_lshlrev_b64 v[32:33], 11, v[216:217]
	v_readlane_b32 s15, v254, 9
	v_cvt_pk_bf16_f32 v26, v34, v35
	v_add_f32_e32 v16, v37, v16
	ds_bpermute_b32 v17, v113, v16
	v_lshl_add_u64 v[32:33], v[32:33], 1, s[14:15]
	v_lshl_add_u64 v[32:33], v[212:213], 1, v[32:33]
	v_cvt_pk_bf16_f32 v27, v36, v27
	flat_store_dwordx4 v[32:33], v[24:27] sc1
	v_cvt_pk_bf16_f32 v18, v20, v21
	v_cvt_pk_bf16_f32 v19, v22, v23
	v_cvt_pk_bf16_f32 v20, v28, v29
	v_cvt_pk_bf16_f32 v21, v30, v31
	flat_store_dwordx4 v[32:33], v[18:21] offset:256 sc1
	s_and_saveexec_b64 s[14:15], s[4:5]
	s_cbranch_execz .LBB0_215
	s_waitcnt lgkmcnt(0)
	v_add_f32_e32 v16, v16, v17
	v_mul_f32_e32 v16, 0x49800000, v16
	v_trunc_f32_e32 v16, v16
	v_mul_f32_e32 v17, 0x2f800000, v16
	v_floor_f32_e32 v17, v17
	v_fmac_f32_e32 v16, 0xcf800000, v17
	v_cvt_u32_f32_e32 v16, v16
	v_cvt_u32_f32_e32 v17, v17
	v_readlane_b32 s16, v254, 39
	v_readlane_b32 s17, v254, 40
	s_nop 1
	v_lshl_add_u64 v[18:19], v[216:217], 3, s[16:17]
	flat_atomic_add_x2 v[18:19], v[16:17]
.LBB0_215:
	s_or_b64 exec, exec, s[14:15]
	v_and_b32_e32 v19, 0xffff0000, v140
	v_lshlrev_b32_e32 v18, 16, v140
	v_and_b32_e32 v21, 0xffff0000, v141
	v_add_f32_e32 v13, v13, v19
	v_lshlrev_b32_e32 v20, 16, v141
	v_add_f32_e32 v12, v12, v18
	v_add_f32_e32 v15, v15, v21
	v_mul_f32_e32 v21, v13, v13
	v_add_f32_e32 v14, v14, v20
	v_fmac_f32_e32 v21, v12, v12
	v_lshlrev_b32_e32 v22, 16, v142
	v_fmac_f32_e32 v21, v14, v14
	v_and_b32_e32 v23, 0xffff0000, v142
	v_add_f32_e32 v18, v8, v22
	v_fmac_f32_e32 v21, v15, v15
	v_lshlrev_b32_e32 v24, 16, v143
	v_add_f32_e32 v19, v9, v23
	v_fmac_f32_e32 v21, v18, v18
	v_and_b32_e32 v25, 0xffff0000, v143
	v_add_f32_e32 v20, v10, v24
	v_fmac_f32_e32 v21, v19, v19
	v_add_f32_e32 v11, v11, v25
	v_fmac_f32_e32 v21, v20, v20
	v_lshlrev_b32_e32 v10, 16, v132
	v_fmac_f32_e32 v21, v11, v11
	v_cvt_pk_bf16_f32 v8, v12, v13
	v_and_b32_e32 v12, 0xffff0000, v132
	v_add_f32_e32 v4, v4, v10
	v_lshlrev_b32_e32 v13, 16, v133
	v_add_f32_e32 v5, v5, v12
	v_fmac_f32_e32 v21, v4, v4
	v_cvt_pk_bf16_f32 v9, v14, v15
	v_and_b32_e32 v14, 0xffff0000, v133
	v_add_f32_e32 v6, v6, v13
	v_fmac_f32_e32 v21, v5, v5
	v_lshlrev_b32_e32 v15, 16, v134
	v_add_f32_e32 v7, v7, v14
	v_fmac_f32_e32 v21, v6, v6
	v_and_b32_e32 v22, 0xffff0000, v134
	v_add_f32_e32 v12, v0, v15
	v_fmac_f32_e32 v21, v7, v7
	v_lshlrev_b32_e32 v23, 16, v135
	v_add_f32_e32 v13, v1, v22
	v_fmac_f32_e32 v21, v12, v12
	v_and_b32_e32 v24, 0xffff0000, v135
	v_add_f32_e32 v14, v2, v23
	v_fmac_f32_e32 v21, v13, v13
	v_add_f32_e32 v15, v3, v24
	v_fmac_f32_e32 v21, v14, v14
	v_fmac_f32_e32 v21, v15, v15
	ds_bpermute_b32 v0, v112, v21
	v_readlane_b32 s14, v254, 8
	s_waitcnt lgkmcnt(0)
	v_lshlrev_b64 v[16:17], 11, v[214:215]
	v_readlane_b32 s15, v254, 9
	v_cvt_pk_bf16_f32 v10, v18, v19
	v_add_f32_e32 v0, v21, v0
	ds_bpermute_b32 v1, v113, v0
	v_lshl_add_u64 v[16:17], v[16:17], 1, s[14:15]
	v_lshl_add_u64 v[16:17], v[212:213], 1, v[16:17]
	v_cvt_pk_bf16_f32 v11, v20, v11
	flat_store_dwordx4 v[16:17], v[8:11] sc1
	v_cvt_pk_bf16_f32 v2, v4, v5
	v_cvt_pk_bf16_f32 v3, v6, v7
	v_cvt_pk_bf16_f32 v4, v12, v13
	v_cvt_pk_bf16_f32 v5, v14, v15
	flat_store_dwordx4 v[16:17], v[2:5] offset:256 sc1
	s_and_saveexec_b64 s[14:15], s[4:5]
	s_cbranch_execz .LBB0_186
	s_waitcnt lgkmcnt(0)
	v_add_f32_e32 v0, v0, v1
	v_mul_f32_e32 v0, 0x49800000, v0
	v_trunc_f32_e32 v0, v0
	v_mul_f32_e32 v1, 0x2f800000, v0
	v_floor_f32_e32 v1, v1
	v_fmac_f32_e32 v0, 0xcf800000, v1
	v_cvt_u32_f32_e32 v0, v0
	v_cvt_u32_f32_e32 v1, v1
	v_readlane_b32 s16, v254, 39
	v_readlane_b32 s17, v254, 40
	s_nop 1
	v_lshl_add_u64 v[2:3], v[214:215], 3, s[16:17]
	flat_atomic_add_x2 v[2:3], v[0:1]
	s_branch .LBB0_186

; #define LAS __attribute__((address_space(3)))
; __device__ __forceinline__ unsigned cvt_pk_bf16(float lo, float hi) { unsigned r; asm volatile("v_cvt_pk_bf16_f32 %0, %1, %2" : "=v"(r) : "v"(lo), "v"(hi)); return r; }
; #define PG8_WAIT_V(n) asm volatile("s_waitcnt vmcnt(" #n ")" ::: "memory")
; #define PG8_BAR __builtin_amdgcn_s_barrier()
; template <class Epi>
; __device__ __forceinline__ void gemm_phase(LAS unsigned char* lds, const Gemm g, const StaticOrder& S, const Epi& E) {
;     ...
;     PG8_WAIT_V(0);
;     if (wr == 0) PG8_BAR;
;     PG8_BAR;
;     __device__ __forceinline__ void operator()(const f32x4 (&acc)[2][2][4][2], const Unit& u, int wr, int wc, int fr, int fq, LAS unsigned char* lds, int par, int npm, int tid) const {
;         const int row0 = u.pm * BM + wr * 64 + fr, col0 = u.pn * BM + wc * 32 + 8 * fq;
;         unsigned long long nx = 0ull; if (npm >= 0) nx = prefetch(npm, tid);
; #pragma unroll
;         for (int ai = 0; ai < 2; ++ai)
; #pragma unroll
;             for (int m = 0; m < 4; ++m) { const int row = row0 + ai * HALF + m * 16; bf16_t* rowp = O + (size_t)row * ldc + col0;
;                 const float rstd = *(const LAS float*)(lds + 131072 + par * 1024 + (wr * 64 + fr + ai * HALF + m * 16) * 4);
; #pragma unroll
;                 for (int bj = 0; bj < 2; ++bj) { f32x4 v0 = acc[ai][bj][m][0] * rstd, v1 = acc[ai][bj][m][1] * rstd;
;                     if (ACT == 1) {
; #pragma unroll
;                         for (int j = 0; j < 4; ++j) { const float a = fmaxf(v0[j], 0.f), b = fmaxf(v1[j], 0.f); v0[j] = a * a; v1[j] = b * b; } }
;                     u32x4 w; w.x = cvt_pk_bf16(v0[0], v0[1]); w.y = cvt_pk_bf16(v0[2], v0[3]); w.z = cvt_pk_bf16(v1[0], v1[1]); w.w = cvt_pk_bf16(v1[2], v1[3]);
;                     *(u32x4*)(rowp + bj * HALF) = w; } }
.LBB0_401:
	v_lshl_add_u32 v130, v138, 2, 0
	v_add_u32_e32 v137, 0x20000, v130
	ds_read_b32 v130, v137
	v_readlane_b32 s4, v254, 23
	v_lshl_or_b32 v128, s35, 8, v139
	v_readlane_b32 s5, v254, 24
	v_or_b32_e32 v131, s36, v128
	v_lshl_add_u32 v136, s34, 8, v138
	v_mov_b64_e32 v[128:129], s[4:5]
	s_movk_i32 s6, 0x2400
	v_mad_i64_i32 v[132:133], s[4:5], v136, s6, v[128:129]
	v_lshlrev_b32_e32 v194, 1, v131
	v_lshl_add_u64 v[132:133], v[132:133], 0, v[194:195]
	s_waitcnt lgkmcnt(0)
	v_pk_mul_f32 v[126:127], v[126:127], v[130:131] op_sel_hi:[1,0]
	v_pk_mul_f32 v[124:125], v[124:125], v[130:131] op_sel_hi:[1,0]
	v_pk_mul_f32 v[134:135], v[122:123], v[130:131] op_sel_hi:[1,0]
	v_pk_mul_f32 v[122:123], v[120:121], v[130:131] op_sel_hi:[1,0]
	v_cvt_pk_bf16_f32 v120, v124, v125
	v_cvt_pk_bf16_f32 v121, v126, v127
	v_pk_mul_f32 v[118:119], v[118:119], v[130:131] op_sel_hi:[1,0]
	v_cvt_pk_bf16_f32 v122, v122, v123
	v_cvt_pk_bf16_f32 v123, v134, v135
	flat_store_dwordx4 v[132:133], v[120:123] sc1
	v_pk_mul_f32 v[116:117], v[116:117], v[130:131] op_sel_hi:[1,0]
	s_cmpk_lt_u32 s33, 0x100
	v_pk_mul_f32 v[120:121], v[114:115], v[130:131] op_sel_hi:[1,0]
	v_pk_mul_f32 v[114:115], v[112:113], v[130:131] op_sel_hi:[1,0]
	v_cvt_pk_bf16_f32 v112, v116, v117
	v_cvt_pk_bf16_f32 v113, v118, v119
	s_nop 0
	v_cvt_pk_bf16_f32 v114, v114, v115
	v_cvt_pk_bf16_f32 v115, v120, v121
	flat_store_dwordx4 v[132:133], v[112:115] offset:256 sc1
	ds_read_b32 v112, v137 offset:64
	s_nop 0
	v_or_b32_e32 v113, 16, v136
	v_mad_i64_i32 v[114:115], s[4:5], v113, s6, v[128:129]
	v_lshl_add_u64 v[114:115], v[114:115], 0, v[194:195]
	s_waitcnt lgkmcnt(0)
	v_pk_mul_f32 v[110:111], v[110:111], v[112:113] op_sel_hi:[1,0]
	v_pk_mul_f32 v[108:109], v[108:109], v[112:113] op_sel_hi:[1,0]
	v_pk_mul_f32 v[116:117], v[106:107], v[112:113] op_sel_hi:[1,0]
	v_pk_mul_f32 v[106:107], v[104:105], v[112:113] op_sel_hi:[1,0]
	v_cvt_pk_bf16_f32 v104, v108, v109
	v_cvt_pk_bf16_f32 v105, v110, v111
	v_pk_mul_f32 v[102:103], v[102:103], v[112:113] op_sel_hi:[1,0]
	v_cvt_pk_bf16_f32 v106, v106, v107
	v_cvt_pk_bf16_f32 v107, v116, v117
	flat_store_dwordx4 v[114:115], v[104:107] sc1
	v_pk_mul_f32 v[100:101], v[100:101], v[112:113] op_sel_hi:[1,0]
	s_nop 0
	v_pk_mul_f32 v[104:105], v[98:99], v[112:113] op_sel_hi:[1,0]
	v_pk_mul_f32 v[98:99], v[96:97], v[112:113] op_sel_hi:[1,0]
	v_cvt_pk_bf16_f32 v96, v100, v101
	v_cvt_pk_bf16_f32 v97, v102, v103
	s_nop 0
	v_cvt_pk_bf16_f32 v98, v98, v99
	v_cvt_pk_bf16_f32 v99, v104, v105
	flat_store_dwordx4 v[114:115], v[96:99] offset:256 sc1
	ds_read_b32 v96, v137 offset:128
	s_nop 0
	v_or_b32_e32 v97, 32, v136
	v_mad_i64_i32 v[98:99], s[4:5], v97, s6, v[128:129]
	v_lshl_add_u64 v[98:99], v[98:99], 0, v[194:195]
	s_waitcnt lgkmcnt(0)
	v_pk_mul_f32 v[94:95], v[94:95], v[96:97] op_sel_hi:[1,0]
	v_pk_mul_f32 v[92:93], v[92:93], v[96:97] op_sel_hi:[1,0]
	v_pk_mul_f32 v[100:101], v[90:91], v[96:97] op_sel_hi:[1,0]
	v_pk_mul_f32 v[90:91], v[88:89], v[96:97] op_sel_hi:[1,0]
	v_cvt_pk_bf16_f32 v88, v92, v93
	v_cvt_pk_bf16_f32 v89, v94, v95
	v_pk_mul_f32 v[86:87], v[86:87], v[96:97] op_sel_hi:[1,0]
	v_cvt_pk_bf16_f32 v90, v90, v91
	v_cvt_pk_bf16_f32 v91, v100, v101
	flat_store_dwordx4 v[98:99], v[88:91] sc1
	v_pk_mul_f32 v[84:85], v[84:85], v[96:97] op_sel_hi:[1,0]
	s_nop 0
	v_pk_mul_f32 v[88:89], v[82:83], v[96:97] op_sel_hi:[1,0]
	v_pk_mul_f32 v[82:83], v[80:81], v[96:97] op_sel_hi:[1,0]
	v_cvt_pk_bf16_f32 v80, v84, v85
	v_cvt_pk_bf16_f32 v81, v86, v87
	s_nop 0
	v_cvt_pk_bf16_f32 v82, v82, v83
	v_cvt_pk_bf16_f32 v83, v88, v89
	flat_store_dwordx4 v[98:99], v[80:83] offset:256 sc1
	ds_read_b32 v80, v137 offset:192
	s_nop 0
	v_or_b32_e32 v81, 48, v136
	v_mad_i64_i32 v[82:83], s[4:5], v81, s6, v[128:129]
	v_lshl_add_u64 v[82:83], v[82:83], 0, v[194:195]
	s_waitcnt lgkmcnt(0)
	v_pk_mul_f32 v[78:79], v[78:79], v[80:81] op_sel_hi:[1,0]
	v_pk_mul_f32 v[76:77], v[76:77], v[80:81] op_sel_hi:[1,0]
	v_pk_mul_f32 v[84:85], v[74:75], v[80:81] op_sel_hi:[1,0]
	v_pk_mul_f32 v[74:75], v[72:73], v[80:81] op_sel_hi:[1,0]
	v_cvt_pk_bf16_f32 v72, v76, v77
	v_cvt_pk_bf16_f32 v73, v78, v79
	v_pk_mul_f32 v[70:71], v[70:71], v[80:81] op_sel_hi:[1,0]
	v_cvt_pk_bf16_f32 v74, v74, v75
	v_cvt_pk_bf16_f32 v75, v84, v85
	flat_store_dwordx4 v[82:83], v[72:75] sc1
	v_pk_mul_f32 v[68:69], v[68:69], v[80:81] op_sel_hi:[1,0]
	s_nop 0
	v_pk_mul_f32 v[72:73], v[66:67], v[80:81] op_sel_hi:[1,0]
	v_pk_mul_f32 v[66:67], v[64:65], v[80:81] op_sel_hi:[1,0]
	v_cvt_pk_bf16_f32 v64, v68, v69
	v_cvt_pk_bf16_f32 v65, v70, v71
	s_nop 0
	v_cvt_pk_bf16_f32 v66, v66, v67
	v_cvt_pk_bf16_f32 v67, v72, v73
	flat_store_dwordx4 v[82:83], v[64:67] offset:256 sc1
	ds_read_b32 v64, v137 offset:512
	s_nop 0
	v_add_u32_e32 v65, 0x80, v136
	v_mad_i64_i32 v[66:67], s[4:5], v65, s6, v[128:129]
	v_lshl_add_u64 v[66:67], v[66:67], 0, v[194:195]
	s_waitcnt lgkmcnt(0)
; #define LAS __attribute__((address_space(3)))
; __device__ __forceinline__ unsigned cvt_pk_bf16(float lo, float hi) { unsigned r; asm volatile("v_cvt_pk_bf16_f32 %0, %1, %2" : "=v"(r) : "v"(lo), "v"(hi)); return r; }
; #define PG8_WAIT_V(n) asm volatile("s_waitcnt vmcnt(" #n ")" ::: "memory")
; #define PG8_BAR __builtin_amdgcn_s_barrier()
; template <class Epi>
; __device__ __forceinline__ void gemm_phase(LAS unsigned char* lds, const Gemm g, const StaticOrder& S, const Epi& E) {
;     ...
;     PG8_WAIT_V(0);
;     if (wr == 0) PG8_BAR;
;     PG8_BAR;
;     __device__ __forceinline__ void operator()(const f32x4 (&acc)[2][2][4][2], const Unit& u, int wr, int wc, int fr, int fq, LAS unsigned char* lds, int par, int npm, int tid) const {
;     ...
;             for (int m = 0; m < 4; ++m) { const int row = row0 + ai * HALF + m * 16; bf16_t* rowp = O + (size_t)row * ldc + col0;
;                 const float rstd = *(const LAS float*)(lds + 131072 + par * 1024 + (wr * 64 + fr + ai * HALF + m * 16) * 4);
; #pragma unroll
;                 for (int bj = 0; bj < 2; ++bj) { f32x4 v0 = acc[ai][bj][m][0] * rstd, v1 = acc[ai][bj][m][1] * rstd;
;                     if (ACT == 1) {
; #pragma unroll
;                         for (int j = 0; j < 4; ++j) { const float a = fmaxf(v0[j], 0.f), b = fmaxf(v1[j], 0.f); v0[j] = a * a; v1[j] = b * b; } }
;                     u32x4 w; w.x = cvt_pk_bf16(v0[0], v0[1]); w.y = cvt_pk_bf16(v0[2], v0[3]); w.z = cvt_pk_bf16(v1[0], v1[1]); w.w = cvt_pk_bf16(v1[2], v1[3]);
;                     *(u32x4*)(rowp + bj * HALF) = w; } }
	v_pk_mul_f32 v[62:63], v[62:63], v[64:65] op_sel_hi:[1,0]
	v_pk_mul_f32 v[60:61], v[60:61], v[64:65] op_sel_hi:[1,0]
	v_pk_mul_f32 v[68:69], v[58:59], v[64:65] op_sel_hi:[1,0]
	v_pk_mul_f32 v[58:59], v[56:57], v[64:65] op_sel_hi:[1,0]
	v_cvt_pk_bf16_f32 v56, v60, v61
	v_cvt_pk_bf16_f32 v57, v62, v63
	v_pk_mul_f32 v[54:55], v[54:55], v[64:65] op_sel_hi:[1,0]
	v_cvt_pk_bf16_f32 v58, v58, v59
	v_cvt_pk_bf16_f32 v59, v68, v69
	flat_store_dwordx4 v[66:67], v[56:59] sc1
	v_pk_mul_f32 v[52:53], v[52:53], v[64:65] op_sel_hi:[1,0]
	s_nop 0
	v_pk_mul_f32 v[56:57], v[50:51], v[64:65] op_sel_hi:[1,0]
	v_pk_mul_f32 v[50:51], v[48:49], v[64:65] op_sel_hi:[1,0]
	v_cvt_pk_bf16_f32 v48, v52, v53
	v_cvt_pk_bf16_f32 v49, v54, v55
	s_nop 0
	v_cvt_pk_bf16_f32 v50, v50, v51
	v_cvt_pk_bf16_f32 v51, v56, v57
	flat_store_dwordx4 v[66:67], v[48:51] offset:256 sc1
	ds_read_b32 v48, v137 offset:576
	s_nop 0
	v_add_u32_e32 v49, 0x90, v136
	v_mad_i64_i32 v[50:51], s[4:5], v49, s6, v[128:129]
	v_lshl_add_u64 v[50:51], v[50:51], 0, v[194:195]
	s_waitcnt lgkmcnt(0)
	v_pk_mul_f32 v[46:47], v[46:47], v[48:49] op_sel_hi:[1,0]
	v_pk_mul_f32 v[44:45], v[44:45], v[48:49] op_sel_hi:[1,0]
	v_pk_mul_f32 v[52:53], v[42:43], v[48:49] op_sel_hi:[1,0]
	v_pk_mul_f32 v[42:43], v[40:41], v[48:49] op_sel_hi:[1,0]
	v_cvt_pk_bf16_f32 v40, v44, v45
	v_cvt_pk_bf16_f32 v41, v46, v47
	v_pk_mul_f32 v[38:39], v[38:39], v[48:49] op_sel_hi:[1,0]
	v_cvt_pk_bf16_f32 v42, v42, v43
	v_cvt_pk_bf16_f32 v43, v52, v53
	flat_store_dwordx4 v[50:51], v[40:43] sc1
	v_pk_mul_f32 v[36:37], v[36:37], v[48:49] op_sel_hi:[1,0]
	s_nop 0
	v_pk_mul_f32 v[40:41], v[34:35], v[48:49] op_sel_hi:[1,0]
	v_pk_mul_f32 v[34:35], v[32:33], v[48:49] op_sel_hi:[1,0]
	v_cvt_pk_bf16_f32 v32, v36, v37
	v_cvt_pk_bf16_f32 v33, v38, v39
	s_nop 0
	v_cvt_pk_bf16_f32 v34, v34, v35
	v_cvt_pk_bf16_f32 v35, v40, v41
	flat_store_dwordx4 v[50:51], v[32:35] offset:256 sc1
	ds_read_b32 v32, v137 offset:640
	s_nop 0
	v_add_u32_e32 v33, 0xa0, v136
	v_mad_i64_i32 v[34:35], s[4:5], v33, s6, v[128:129]
	v_lshl_add_u64 v[34:35], v[34:35], 0, v[194:195]
	s_waitcnt lgkmcnt(0)
	v_pk_mul_f32 v[30:31], v[30:31], v[32:33] op_sel_hi:[1,0]
	v_pk_mul_f32 v[28:29], v[28:29], v[32:33] op_sel_hi:[1,0]
	v_pk_mul_f32 v[36:37], v[26:27], v[32:33] op_sel_hi:[1,0]
	v_pk_mul_f32 v[26:27], v[24:25], v[32:33] op_sel_hi:[1,0]
	v_cvt_pk_bf16_f32 v24, v28, v29
	v_cvt_pk_bf16_f32 v25, v30, v31
	v_pk_mul_f32 v[22:23], v[22:23], v[32:33] op_sel_hi:[1,0]
	v_cvt_pk_bf16_f32 v26, v26, v27
	v_cvt_pk_bf16_f32 v27, v36, v37
	flat_store_dwordx4 v[34:35], v[24:27] sc1
	v_pk_mul_f32 v[20:21], v[20:21], v[32:33] op_sel_hi:[1,0]
	s_nop 0
	v_pk_mul_f32 v[24:25], v[18:19], v[32:33] op_sel_hi:[1,0]
	v_pk_mul_f32 v[18:19], v[16:17], v[32:33] op_sel_hi:[1,0]
	v_cvt_pk_bf16_f32 v16, v20, v21
	v_cvt_pk_bf16_f32 v17, v22, v23
	s_nop 0
	v_cvt_pk_bf16_f32 v18, v18, v19
	v_cvt_pk_bf16_f32 v19, v24, v25
	flat_store_dwordx4 v[34:35], v[16:19] offset:256 sc1
	ds_read_b32 v16, v137 offset:704
	s_nop 0
	v_add_u32_e32 v17, 0xb0, v136
	v_mad_i64_i32 v[18:19], s[4:5], v17, s6, v[128:129]
	v_lshl_add_u64 v[18:19], v[18:19], 0, v[194:195]
	s_waitcnt lgkmcnt(0)
	v_pk_mul_f32 v[14:15], v[14:15], v[16:17] op_sel_hi:[1,0]
	v_pk_mul_f32 v[12:13], v[12:13], v[16:17] op_sel_hi:[1,0]
	v_pk_mul_f32 v[20:21], v[10:11], v[16:17] op_sel_hi:[1,0]
	v_pk_mul_f32 v[10:11], v[8:9], v[16:17] op_sel_hi:[1,0]
	v_cvt_pk_bf16_f32 v8, v12, v13
	v_cvt_pk_bf16_f32 v9, v14, v15
	v_pk_mul_f32 v[6:7], v[6:7], v[16:17] op_sel_hi:[1,0]
	v_cvt_pk_bf16_f32 v10, v10, v11
	v_cvt_pk_bf16_f32 v11, v20, v21
	flat_store_dwordx4 v[18:19], v[8:11] sc1
	v_pk_mul_f32 v[4:5], v[4:5], v[16:17] op_sel_hi:[1,0]
	s_nop 0
	v_pk_mul_f32 v[8:9], v[2:3], v[16:17] op_sel_hi:[1,0]
	v_pk_mul_f32 v[2:3], v[0:1], v[16:17] op_sel_hi:[1,0]
	v_cvt_pk_bf16_f32 v0, v4, v5
	v_cvt_pk_bf16_f32 v1, v6, v7
	s_nop 0
	v_cvt_pk_bf16_f32 v2, v2, v3
	v_cvt_pk_bf16_f32 v3, v8, v9
	flat_store_dwordx4 v[18:19], v[0:3] offset:256 sc1
	s_waitcnt vmcnt(0)
	s_cbranch_scc0 .LBB0_403
	s_barrier

; #define LAS __attribute__((address_space(3)))
; __device__ __forceinline__ unsigned cvt_pk_bf16(float lo, float hi) { unsigned r; asm volatile("v_cvt_pk_bf16_f32 %0, %1, %2" : "=v"(r) : "v"(lo), "v"(hi)); return r; }
;     __device__ __forceinline__ void operator()(const f32x4 (&acc)[2][2][4][2], const Unit& u, int wr, int wc, int fr, int fq, LAS unsigned char* lds, int par, int npm, int tid) const {
;         const int row0 = u.pm * BM + wr * 64 + fr, col0 = u.pn * BM + wc * 32 + 8 * fq;
;         unsigned long long nx = 0ull; if (npm >= 0) nx = prefetch(npm, tid);
; #pragma unroll
;         for (int ai = 0; ai < 2; ++ai)
; #pragma unroll
;             for (int m = 0; m < 4; ++m) { const int row = row0 + ai * HALF + m * 16; bf16_t* rowp = O + (size_t)row * ldc + col0;
;                 const float rstd = *(const LAS float*)(lds + 131072 + par * 1024 + (wr * 64 + fr + ai * HALF + m * 16) * 4);
; #pragma unroll
;                 for (int bj = 0; bj < 2; ++bj) { f32x4 v0 = acc[ai][bj][m][0] * rstd, v1 = acc[ai][bj][m][1] * rstd;
;                     if (ACT == 1) {
; #pragma unroll
;                         for (int j = 0; j < 4; ++j) { const float a = fmaxf(v0[j], 0.f), b = fmaxf(v1[j], 0.f); v0[j] = a * a; v1[j] = b * b; } }
;                     u32x4 w; w.x = cvt_pk_bf16(v0[0], v0[1]); w.y = cvt_pk_bf16(v0[2], v0[3]); w.z = cvt_pk_bf16(v1[0], v1[1]); w.w = cvt_pk_bf16(v1[2], v1[3]);
;                     *(u32x4*)(rowp + bj * HALF) = w; } }
.LBB0_531:
	s_or_b64 exec, exec, s[16:17]
	s_lshl_b32 s16, s39, 10
	s_and_b32 s18, s16, 0x400
	v_add_u32_e32 v156, s18, v145
	ds_read_b32 v150, v156
	v_readlane_b32 s16, v254, 23
	v_lshl_or_b32 v140, s38, 8, v147
	v_readlane_b32 s17, v254, 24
	v_lshl_add_u32 v151, s37, 8, v143
	v_ashrrev_i32_e32 v141, 31, v140
	v_mov_b64_e32 v[138:139], s[16:17]
	s_movk_i32 s19, 0x2400
	v_mad_i64_i32 v[152:153], s[16:17], v151, s19, v[138:139]
	v_lshlrev_b64 v[140:141], 1, v[140:141]
	v_lshl_add_u64 v[152:153], v[152:153], 0, v[140:141]
	s_waitcnt lgkmcnt(0)
	v_pk_mul_f32 v[126:127], v[126:127], v[150:151] op_sel_hi:[1,0]
	v_pk_mul_f32 v[124:125], v[124:125], v[150:151] op_sel_hi:[1,0]
	v_pk_mul_f32 v[154:155], v[122:123], v[150:151] op_sel_hi:[1,0]
	v_pk_mul_f32 v[122:123], v[120:121], v[150:151] op_sel_hi:[1,0]
	v_cvt_pk_bf16_f32 v120, v124, v125
	v_cvt_pk_bf16_f32 v121, v126, v127
	v_pk_mul_f32 v[118:119], v[118:119], v[150:151] op_sel_hi:[1,0]
	v_cvt_pk_bf16_f32 v122, v122, v123
	v_cvt_pk_bf16_f32 v123, v154, v155
	flat_store_dwordx4 v[152:153], v[120:123] sc1
	v_pk_mul_f32 v[116:117], v[116:117], v[150:151] op_sel_hi:[1,0]
	s_nop 0
	v_pk_mul_f32 v[120:121], v[114:115], v[150:151] op_sel_hi:[1,0]
	v_pk_mul_f32 v[114:115], v[112:113], v[150:151] op_sel_hi:[1,0]
	v_cvt_pk_bf16_f32 v112, v116, v117
	v_cvt_pk_bf16_f32 v113, v118, v119
	s_nop 0
	v_cvt_pk_bf16_f32 v114, v114, v115
	v_cvt_pk_bf16_f32 v115, v120, v121
	flat_store_dwordx4 v[152:153], v[112:115] offset:256 sc1
	ds_read_b32 v112, v156 offset:64
	s_nop 0
	v_or_b32_e32 v113, 16, v151
	v_mad_i64_i32 v[114:115], s[16:17], v113, s19, v[138:139]
	v_lshl_add_u64 v[114:115], v[114:115], 0, v[140:141]
	s_waitcnt lgkmcnt(0)
	v_pk_mul_f32 v[110:111], v[110:111], v[112:113] op_sel_hi:[1,0]
	v_pk_mul_f32 v[108:109], v[108:109], v[112:113] op_sel_hi:[1,0]
	v_pk_mul_f32 v[116:117], v[106:107], v[112:113] op_sel_hi:[1,0]
	v_pk_mul_f32 v[106:107], v[104:105], v[112:113] op_sel_hi:[1,0]
	v_cvt_pk_bf16_f32 v104, v108, v109
	v_cvt_pk_bf16_f32 v105, v110, v111
	v_pk_mul_f32 v[102:103], v[102:103], v[112:113] op_sel_hi:[1,0]
	v_cvt_pk_bf16_f32 v106, v106, v107
	v_cvt_pk_bf16_f32 v107, v116, v117
	flat_store_dwordx4 v[114:115], v[104:107] sc1
	v_pk_mul_f32 v[100:101], v[100:101], v[112:113] op_sel_hi:[1,0]
	s_nop 0
	v_pk_mul_f32 v[104:105], v[98:99], v[112:113] op_sel_hi:[1,0]
	v_pk_mul_f32 v[98:99], v[96:97], v[112:113] op_sel_hi:[1,0]
	v_cvt_pk_bf16_f32 v96, v100, v101
	v_cvt_pk_bf16_f32 v97, v102, v103
	s_nop 0
	v_cvt_pk_bf16_f32 v98, v98, v99
	v_cvt_pk_bf16_f32 v99, v104, v105
	flat_store_dwordx4 v[114:115], v[96:99] offset:256 sc1
	ds_read_b32 v96, v156 offset:128
	s_nop 0
	v_or_b32_e32 v97, 32, v151
	v_mad_i64_i32 v[98:99], s[16:17], v97, s19, v[138:139]
	v_lshl_add_u64 v[98:99], v[98:99], 0, v[140:141]
	s_waitcnt lgkmcnt(0)
	v_pk_mul_f32 v[94:95], v[94:95], v[96:97] op_sel_hi:[1,0]
	v_pk_mul_f32 v[92:93], v[92:93], v[96:97] op_sel_hi:[1,0]
	v_pk_mul_f32 v[100:101], v[90:91], v[96:97] op_sel_hi:[1,0]
	v_pk_mul_f32 v[90:91], v[88:89], v[96:97] op_sel_hi:[1,0]
	v_cvt_pk_bf16_f32 v88, v92, v93
	v_cvt_pk_bf16_f32 v89, v94, v95
	v_pk_mul_f32 v[86:87], v[86:87], v[96:97] op_sel_hi:[1,0]
	v_cvt_pk_bf16_f32 v90, v90, v91
	v_cvt_pk_bf16_f32 v91, v100, v101
	flat_store_dwordx4 v[98:99], v[88:91] sc1
	v_pk_mul_f32 v[84:85], v[84:85], v[96:97] op_sel_hi:[1,0]
	s_nop 0
	v_pk_mul_f32 v[88:89], v[82:83], v[96:97] op_sel_hi:[1,0]
	v_pk_mul_f32 v[82:83], v[80:81], v[96:97] op_sel_hi:[1,0]
	v_cvt_pk_bf16_f32 v80, v84, v85
	v_cvt_pk_bf16_f32 v81, v86, v87
	s_nop 0
	v_cvt_pk_bf16_f32 v82, v82, v83
	v_cvt_pk_bf16_f32 v83, v88, v89
	flat_store_dwordx4 v[98:99], v[80:83] offset:256 sc1
	ds_read_b32 v80, v156 offset:192
	s_nop 0
	v_or_b32_e32 v81, 48, v151
	v_mad_i64_i32 v[82:83], s[16:17], v81, s19, v[138:139]
	v_lshl_add_u64 v[82:83], v[82:83], 0, v[140:141]
	s_waitcnt lgkmcnt(0)
	v_pk_mul_f32 v[78:79], v[78:79], v[80:81] op_sel_hi:[1,0]
	v_pk_mul_f32 v[76:77], v[76:77], v[80:81] op_sel_hi:[1,0]
	v_pk_mul_f32 v[84:85], v[74:75], v[80:81] op_sel_hi:[1,0]
	v_pk_mul_f32 v[74:75], v[72:73], v[80:81] op_sel_hi:[1,0]
	v_cvt_pk_bf16_f32 v72, v76, v77
	v_cvt_pk_bf16_f32 v73, v78, v79
	v_pk_mul_f32 v[70:71], v[70:71], v[80:81] op_sel_hi:[1,0]
	v_cvt_pk_bf16_f32 v74, v74, v75
	v_cvt_pk_bf16_f32 v75, v84, v85
	flat_store_dwordx4 v[82:83], v[72:75] sc1
	v_pk_mul_f32 v[68:69], v[68:69], v[80:81] op_sel_hi:[1,0]
	s_nop 0
	v_pk_mul_f32 v[72:73], v[66:67], v[80:81] op_sel_hi:[1,0]
	v_pk_mul_f32 v[66:67], v[64:65], v[80:81] op_sel_hi:[1,0]
	v_cvt_pk_bf16_f32 v64, v68, v69
	v_cvt_pk_bf16_f32 v65, v70, v71
	s_nop 0
	v_cvt_pk_bf16_f32 v66, v66, v67
	v_cvt_pk_bf16_f32 v67, v72, v73
	flat_store_dwordx4 v[82:83], v[64:67] offset:256 sc1
	ds_read_b32 v64, v156 offset:512
	s_nop 0
	v_add_u32_e32 v65, 0x80, v151
	v_mad_i64_i32 v[66:67], s[16:17], v65, s19, v[138:139]
	v_lshl_add_u64 v[66:67], v[66:67], 0, v[140:141]
	s_waitcnt lgkmcnt(0)
; #define LAS __attribute__((address_space(3)))
; __device__ __forceinline__ unsigned cvt_pk_bf16(float lo, float hi) { unsigned r; asm volatile("v_cvt_pk_bf16_f32 %0, %1, %2" : "=v"(r) : "v"(lo), "v"(hi)); return r; }
;     __device__ __forceinline__ void stash(unsigned long long v, LAS unsigned char* lds, int par, int tid) const { if (tid < 256) *(LAS float*)(lds + 131072 + par * 1024 + tid * 4) = rsqrtf((float)v * (1.f / (1048576.f * DM)) + EPS_); }
;     __device__ __forceinline__ void operator()(const f32x4 (&acc)[2][2][4][2], const Unit& u, int wr, int wc, int fr, int fq, LAS unsigned char* lds, int par, int npm, int tid) const {
;     ...
;             for (int m = 0; m < 4; ++m) { const int row = row0 + ai * HALF + m * 16; bf16_t* rowp = O + (size_t)row * ldc + col0;
;                 const float rstd = *(const LAS float*)(lds + 131072 + par * 1024 + (wr * 64 + fr + ai * HALF + m * 16) * 4);
; #pragma unroll
;                 for (int bj = 0; bj < 2; ++bj) { f32x4 v0 = acc[ai][bj][m][0] * rstd, v1 = acc[ai][bj][m][1] * rstd;
;                     if (ACT == 1) {
; #pragma unroll
;                         for (int j = 0; j < 4; ++j) { const float a = fmaxf(v0[j], 0.f), b = fmaxf(v1[j], 0.f); v0[j] = a * a; v1[j] = b * b; } }
;                     u32x4 w; w.x = cvt_pk_bf16(v0[0], v0[1]); w.y = cvt_pk_bf16(v0[2], v0[3]); w.z = cvt_pk_bf16(v1[0], v1[1]); w.w = cvt_pk_bf16(v1[2], v1[3]);
;                     *(u32x4*)(rowp + bj * HALF) = w; } }
;         if (npm >= 0) stash(nx, lds, par ^ 1, tid);
	v_pk_mul_f32 v[62:63], v[62:63], v[64:65] op_sel_hi:[1,0]
	v_pk_mul_f32 v[60:61], v[60:61], v[64:65] op_sel_hi:[1,0]
	v_pk_mul_f32 v[68:69], v[58:59], v[64:65] op_sel_hi:[1,0]
	v_pk_mul_f32 v[58:59], v[56:57], v[64:65] op_sel_hi:[1,0]
	v_cvt_pk_bf16_f32 v56, v60, v61
	v_cvt_pk_bf16_f32 v57, v62, v63
	v_pk_mul_f32 v[54:55], v[54:55], v[64:65] op_sel_hi:[1,0]
	v_cvt_pk_bf16_f32 v58, v58, v59
	v_cvt_pk_bf16_f32 v59, v68, v69
	flat_store_dwordx4 v[66:67], v[56:59] sc1
	v_pk_mul_f32 v[52:53], v[52:53], v[64:65] op_sel_hi:[1,0]
	s_nop 0
	v_pk_mul_f32 v[56:57], v[50:51], v[64:65] op_sel_hi:[1,0]
	v_pk_mul_f32 v[50:51], v[48:49], v[64:65] op_sel_hi:[1,0]
	v_cvt_pk_bf16_f32 v48, v52, v53
	v_cvt_pk_bf16_f32 v49, v54, v55
	s_nop 0
	v_cvt_pk_bf16_f32 v50, v50, v51
	v_cvt_pk_bf16_f32 v51, v56, v57
	flat_store_dwordx4 v[66:67], v[48:51] offset:256 sc1
	ds_read_b32 v48, v156 offset:576
	s_nop 0
	v_add_u32_e32 v49, 0x90, v151
	v_mad_i64_i32 v[50:51], s[16:17], v49, s19, v[138:139]
	v_lshl_add_u64 v[50:51], v[50:51], 0, v[140:141]
	s_waitcnt lgkmcnt(0)
	v_pk_mul_f32 v[46:47], v[46:47], v[48:49] op_sel_hi:[1,0]
	v_pk_mul_f32 v[44:45], v[44:45], v[48:49] op_sel_hi:[1,0]
	v_pk_mul_f32 v[52:53], v[42:43], v[48:49] op_sel_hi:[1,0]
	v_pk_mul_f32 v[42:43], v[40:41], v[48:49] op_sel_hi:[1,0]
	v_cvt_pk_bf16_f32 v40, v44, v45
	v_cvt_pk_bf16_f32 v41, v46, v47
	v_pk_mul_f32 v[38:39], v[38:39], v[48:49] op_sel_hi:[1,0]
	v_cvt_pk_bf16_f32 v42, v42, v43
	v_cvt_pk_bf16_f32 v43, v52, v53
	flat_store_dwordx4 v[50:51], v[40:43] sc1
	v_pk_mul_f32 v[36:37], v[36:37], v[48:49] op_sel_hi:[1,0]
	s_nop 0
	v_pk_mul_f32 v[40:41], v[34:35], v[48:49] op_sel_hi:[1,0]
	v_pk_mul_f32 v[34:35], v[32:33], v[48:49] op_sel_hi:[1,0]
	v_cvt_pk_bf16_f32 v32, v36, v37
	v_cvt_pk_bf16_f32 v33, v38, v39
	s_nop 0
	v_cvt_pk_bf16_f32 v34, v34, v35
	v_cvt_pk_bf16_f32 v35, v40, v41
	flat_store_dwordx4 v[50:51], v[32:35] offset:256 sc1
	ds_read_b32 v32, v156 offset:640
	s_nop 0
	v_add_u32_e32 v33, 0xa0, v151
	v_mad_i64_i32 v[34:35], s[16:17], v33, s19, v[138:139]
	v_lshl_add_u64 v[34:35], v[34:35], 0, v[140:141]
	s_waitcnt lgkmcnt(0)
	v_pk_mul_f32 v[30:31], v[30:31], v[32:33] op_sel_hi:[1,0]
	v_pk_mul_f32 v[28:29], v[28:29], v[32:33] op_sel_hi:[1,0]
	v_pk_mul_f32 v[36:37], v[26:27], v[32:33] op_sel_hi:[1,0]
	v_pk_mul_f32 v[26:27], v[24:25], v[32:33] op_sel_hi:[1,0]
	v_cvt_pk_bf16_f32 v24, v28, v29
	v_cvt_pk_bf16_f32 v25, v30, v31
	v_pk_mul_f32 v[22:23], v[22:23], v[32:33] op_sel_hi:[1,0]
	v_cvt_pk_bf16_f32 v26, v26, v27
	v_cvt_pk_bf16_f32 v27, v36, v37
	flat_store_dwordx4 v[34:35], v[24:27] sc1
	v_pk_mul_f32 v[20:21], v[20:21], v[32:33] op_sel_hi:[1,0]
	s_nop 0
	v_pk_mul_f32 v[24:25], v[18:19], v[32:33] op_sel_hi:[1,0]
	v_pk_mul_f32 v[18:19], v[16:17], v[32:33] op_sel_hi:[1,0]
	v_cvt_pk_bf16_f32 v16, v20, v21
	v_cvt_pk_bf16_f32 v17, v22, v23
	s_nop 0
	v_cvt_pk_bf16_f32 v18, v18, v19
	v_cvt_pk_bf16_f32 v19, v24, v25
	flat_store_dwordx4 v[34:35], v[16:19] offset:256 sc1
	ds_read_b32 v16, v156 offset:704
	s_nop 0
	v_add_u32_e32 v17, 0xb0, v151
	v_mad_i64_i32 v[18:19], s[16:17], v17, s19, v[138:139]
	v_lshl_add_u64 v[18:19], v[18:19], 0, v[140:141]
	s_waitcnt lgkmcnt(0)
	v_pk_mul_f32 v[14:15], v[14:15], v[16:17] op_sel_hi:[1,0]
	v_pk_mul_f32 v[12:13], v[12:13], v[16:17] op_sel_hi:[1,0]
	v_pk_mul_f32 v[20:21], v[10:11], v[16:17] op_sel_hi:[1,0]
	v_pk_mul_f32 v[10:11], v[8:9], v[16:17] op_sel_hi:[1,0]
	v_cvt_pk_bf16_f32 v8, v12, v13
	v_cvt_pk_bf16_f32 v9, v14, v15
	v_pk_mul_f32 v[6:7], v[6:7], v[16:17] op_sel_hi:[1,0]
	v_cvt_pk_bf16_f32 v10, v10, v11
	v_cvt_pk_bf16_f32 v11, v20, v21
	flat_store_dwordx4 v[18:19], v[8:11] sc1
	v_pk_mul_f32 v[4:5], v[4:5], v[16:17] op_sel_hi:[1,0]
	s_nop 0
	v_pk_mul_f32 v[8:9], v[2:3], v[16:17] op_sel_hi:[1,0]
	v_pk_mul_f32 v[2:3], v[0:1], v[16:17] op_sel_hi:[1,0]
	v_cvt_pk_bf16_f32 v0, v4, v5
	v_cvt_pk_bf16_f32 v1, v6, v7
	s_nop 0
	v_cvt_pk_bf16_f32 v2, v2, v3
	v_cvt_pk_bf16_f32 v3, v8, v9
	flat_store_dwordx4 v[18:19], v[0:3] offset:256 sc1
	s_and_saveexec_b64 s[16:17], s[14:15]
	s_cbranch_execz .LBB0_514
	s_xor_b32 s14, s18, 0x400
	v_add_u32_e32 v0, s14, v146
	s_mov_b32 s14, 0x800000
	v_cmp_gt_f32_e32 vcc, s14, v149
	v_mul_f32_e32 v1, 0x4b800000, v149
	s_nop 0
	v_cndmask_b32_e32 v1, v149, v1, vcc
	v_rsq_f32_e32 v1, v1
	s_nop 0
	v_mul_f32_e32 v2, 0x45800000, v1
	v_cndmask_b32_e32 v1, v1, v2, vcc
	ds_write_b32 v0, v1
	s_branch .LBB0_514
